# plus: phase 9 row-rstd prologue loops unrolled with 16 row loads in flight instead of 4 loads and a full drain per step
# baseline (speedup 1.0000x reference)
;   DI bf16_t* z() const { return (bf16_t*)(ws + OFF_Z); }
; DI float bflo(unsigned u) { return __uint_as_float(u << 16); }
; DI float bfhi(unsigned u) { return __uint_as_float(u & 0xffff0000u); }
; DI int otid() { int t = threadIdx.x; asm volatile("" : "+v"(t)); return t; }
; DI void row_rstd(const bf16_t* __restrict__ A, int lda, int K, int m0, float* rs) {
;   const int tid = otid();
;   const bf16_t* r = A + (size_t)(m0 + (tid >> 1)) * lda + (tid & 1) * (K / 2);
;   float ss = 0.f;
;   for (int c = 0; c < K / 2; c += 8) {
;     const u32x4 v = *(const u32x4*)(r + c);
;     ss += bflo(v.x) * bflo(v.x) + bfhi(v.x) * bfhi(v.x) + bflo(v.y) * bflo(v.y) + bfhi(v.y) * bfhi(v.y) +
;           bflo(v.z) * bflo(v.z) + bfhi(v.z) * bfhi(v.z) + bflo(v.w) * bflo(v.w) + bfhi(v.w) * bfhi(v.w);
;   }
.LBB0_980:
	global_load_dwordx4 v[44:47], v[0:1], off offset:-32
	global_load_dwordx4 v[40:43], v[0:1], off offset:-16
	global_load_dwordx4 v[36:39], v[0:1], off
	global_load_dwordx4 v[32:35], v[0:1], off offset:16
	global_load_dwordx4 v[60:63], v[0:1], off offset:32
	global_load_dwordx4 v[56:59], v[0:1], off offset:48
	global_load_dwordx4 v[52:55], v[0:1], off offset:64
	global_load_dwordx4 v[48:51], v[0:1], off offset:80
	global_load_dwordx4 v[76:79], v[0:1], off offset:96
	global_load_dwordx4 v[72:75], v[0:1], off offset:112
	global_load_dwordx4 v[68:71], v[0:1], off offset:128
	global_load_dwordx4 v[64:67], v[0:1], off offset:144
	global_load_dwordx4 v[92:95], v[0:1], off offset:160
	global_load_dwordx4 v[88:91], v[0:1], off offset:176
	global_load_dwordx4 v[84:87], v[0:1], off offset:192
	global_load_dwordx4 v[80:83], v[0:1], off offset:208
	s_waitcnt vmcnt(12)
	v_lshlrev_b32_e32 v22, 16, v44
	v_and_b32_e32 v23, 0xffff0000, v44
	v_pk_mul_f32 v[22:23], v[22:23], v[22:23]
	v_and_b32_e32 v44, 0xffff0000, v45
	v_lshlrev_b32_e32 v45, 16, v45
	v_pk_mul_f32 v[44:45], v[44:45], v[44:45]
	v_add_f32_e32 v5, v22, v23
	v_and_b32_e32 v24, 0xffff0000, v46
	v_lshlrev_b32_e32 v25, 16, v46
	v_add_f32_e32 v5, v45, v5
	v_pk_mul_f32 v[24:25], v[24:25], v[24:25]
	v_add_f32_e32 v5, v44, v5
	v_and_b32_e32 v46, 0xffff0000, v47
	v_lshlrev_b32_e32 v47, 16, v47
	v_add_f32_e32 v5, v25, v5
	v_pk_mul_f32 v[46:47], v[46:47], v[46:47]
	v_add_f32_e32 v5, v24, v5
	v_add_f32_e32 v5, v47, v5
	v_add_f32_e32 v5, v46, v5
	v_add_f32_e32 v46, v4, v5
	v_lshlrev_b32_e32 v4, 16, v40
	v_and_b32_e32 v5, 0xffff0000, v40
	v_pk_mul_f32 v[4:5], v[4:5], v[4:5]
	v_and_b32_e32 v40, 0xffff0000, v41
	v_lshlrev_b32_e32 v41, 16, v41
	v_pk_mul_f32 v[40:41], v[40:41], v[40:41]
	v_add_f32_e32 v4, v4, v5
	v_and_b32_e32 v44, 0xffff0000, v42
	v_lshlrev_b32_e32 v45, 16, v42
	v_add_f32_e32 v4, v41, v4
	v_pk_mul_f32 v[44:45], v[44:45], v[44:45]
	v_add_f32_e32 v4, v40, v4
	v_and_b32_e32 v42, 0xffff0000, v43
	v_lshlrev_b32_e32 v43, 16, v43
	v_add_f32_e32 v4, v45, v4
	v_pk_mul_f32 v[42:43], v[42:43], v[42:43]
	v_add_f32_e32 v4, v44, v4
	v_add_f32_e32 v4, v43, v4
	v_add_f32_e32 v4, v42, v4
	v_add_f32_e32 v42, v46, v4
	v_lshlrev_b32_e32 v4, 16, v36
	v_and_b32_e32 v5, 0xffff0000, v36
	v_pk_mul_f32 v[4:5], v[4:5], v[4:5]
	v_and_b32_e32 v36, 0xffff0000, v37
	v_lshlrev_b32_e32 v37, 16, v37
	v_pk_mul_f32 v[36:37], v[36:37], v[36:37]
	v_add_f32_e32 v4, v4, v5
	v_and_b32_e32 v40, 0xffff0000, v38
	v_lshlrev_b32_e32 v41, 16, v38
	v_add_f32_e32 v4, v37, v4
	v_pk_mul_f32 v[40:41], v[40:41], v[40:41]
	v_add_f32_e32 v4, v36, v4
	v_and_b32_e32 v38, 0xffff0000, v39
	v_lshlrev_b32_e32 v39, 16, v39
	v_add_f32_e32 v4, v41, v4
	v_pk_mul_f32 v[38:39], v[38:39], v[38:39]
	v_add_f32_e32 v4, v40, v4
	v_add_f32_e32 v4, v39, v4
	v_add_f32_e32 v4, v38, v4
	v_add_f32_e32 v38, v42, v4
	v_lshlrev_b32_e32 v4, 16, v32
	v_and_b32_e32 v5, 0xffff0000, v32
	v_pk_mul_f32 v[4:5], v[4:5], v[4:5]
	v_and_b32_e32 v32, 0xffff0000, v33
	v_lshlrev_b32_e32 v33, 16, v33
	v_pk_mul_f32 v[32:33], v[32:33], v[32:33]
	v_add_f32_e32 v4, v4, v5
	v_and_b32_e32 v36, 0xffff0000, v34
	v_lshlrev_b32_e32 v37, 16, v34
	v_add_f32_e32 v4, v33, v4
	v_pk_mul_f32 v[36:37], v[36:37], v[36:37]
	v_add_f32_e32 v4, v32, v4
	v_and_b32_e32 v34, 0xffff0000, v35
	v_lshlrev_b32_e32 v35, 16, v35
	v_add_f32_e32 v4, v37, v4
	v_pk_mul_f32 v[34:35], v[34:35], v[34:35]
	v_add_f32_e32 v4, v36, v4
	v_add_f32_e32 v4, v35, v4
	v_add_f32_e32 v4, v34, v4
	v_add_f32_e32 v4, v38, v4
	s_waitcnt vmcnt(8)
	v_lshlrev_b32_e32 v22, 16, v60
	v_and_b32_e32 v23, 0xffff0000, v60
	v_pk_mul_f32 v[22:23], v[22:23], v[22:23]
	v_and_b32_e32 v60, 0xffff0000, v61
	v_lshlrev_b32_e32 v61, 16, v61
	v_pk_mul_f32 v[60:61], v[60:61], v[60:61]
	v_add_f32_e32 v5, v22, v23
	v_and_b32_e32 v24, 0xffff0000, v62
	v_lshlrev_b32_e32 v25, 16, v62
	v_add_f32_e32 v5, v61, v5
	v_pk_mul_f32 v[24:25], v[24:25], v[24:25]
	v_add_f32_e32 v5, v60, v5
	v_and_b32_e32 v62, 0xffff0000, v63
	v_lshlrev_b32_e32 v63, 16, v63
	v_add_f32_e32 v5, v25, v5
	v_pk_mul_f32 v[62:63], v[62:63], v[62:63]
	v_add_f32_e32 v5, v24, v5
	v_add_f32_e32 v5, v63, v5
	v_add_f32_e32 v5, v62, v5
	v_add_f32_e32 v62, v4, v5
	v_lshlrev_b32_e32 v4, 16, v56
	v_and_b32_e32 v5, 0xffff0000, v56
	v_pk_mul_f32 v[4:5], v[4:5], v[4:5]
	v_and_b32_e32 v56, 0xffff0000, v57
	v_lshlrev_b32_e32 v57, 16, v57
	v_pk_mul_f32 v[56:57], v[56:57], v[56:57]
	v_add_f32_e32 v4, v4, v5
	v_and_b32_e32 v60, 0xffff0000, v58
	v_lshlrev_b32_e32 v61, 16, v58
	v_add_f32_e32 v4, v57, v4
	v_pk_mul_f32 v[60:61], v[60:61], v[60:61]
	v_add_f32_e32 v4, v56, v4
	v_and_b32_e32 v58, 0xffff0000, v59
	v_lshlrev_b32_e32 v59, 16, v59
	v_add_f32_e32 v4, v61, v4
	v_pk_mul_f32 v[58:59], v[58:59], v[58:59]
	v_add_f32_e32 v4, v60, v4
	v_add_f32_e32 v4, v59, v4
	v_add_f32_e32 v4, v58, v4
	v_add_f32_e32 v58, v62, v4
	v_lshlrev_b32_e32 v4, 16, v52
	v_and_b32_e32 v5, 0xffff0000, v52
	v_pk_mul_f32 v[4:5], v[4:5], v[4:5]
	v_and_b32_e32 v52, 0xffff0000, v53
	v_lshlrev_b32_e32 v53, 16, v53
	v_pk_mul_f32 v[52:53], v[52:53], v[52:53]
	v_add_f32_e32 v4, v4, v5
	v_and_b32_e32 v56, 0xffff0000, v54
	v_lshlrev_b32_e32 v57, 16, v54
	v_add_f32_e32 v4, v53, v4
	v_pk_mul_f32 v[56:57], v[56:57], v[56:57]
	v_add_f32_e32 v4, v52, v4
	v_and_b32_e32 v54, 0xffff0000, v55
	v_lshlrev_b32_e32 v55, 16, v55
	v_add_f32_e32 v4, v57, v4
	v_pk_mul_f32 v[54:55], v[54:55], v[54:55]
	v_add_f32_e32 v4, v56, v4
	v_add_f32_e32 v4, v55, v4
	v_add_f32_e32 v4, v54, v4
	v_add_f32_e32 v54, v58, v4
	v_lshlrev_b32_e32 v4, 16, v48
	v_and_b32_e32 v5, 0xffff0000, v48
	v_pk_mul_f32 v[4:5], v[4:5], v[4:5]
	v_and_b32_e32 v48, 0xffff0000, v49
	v_lshlrev_b32_e32 v49, 16, v49
	v_pk_mul_f32 v[48:49], v[48:49], v[48:49]
	v_add_f32_e32 v4, v4, v5
	v_and_b32_e32 v52, 0xffff0000, v50
	v_lshlrev_b32_e32 v53, 16, v50
	v_add_f32_e32 v4, v49, v4
	v_pk_mul_f32 v[52:53], v[52:53], v[52:53]
	v_add_f32_e32 v4, v48, v4
	v_and_b32_e32 v50, 0xffff0000, v51
	v_lshlrev_b32_e32 v51, 16, v51
	v_add_f32_e32 v4, v53, v4
	v_pk_mul_f32 v[50:51], v[50:51], v[50:51]
	v_add_f32_e32 v4, v52, v4
	v_add_f32_e32 v4, v51, v4
	v_add_f32_e32 v4, v50, v4
	v_add_f32_e32 v4, v54, v4
	s_waitcnt vmcnt(4)
;   DI bf16_t* z() const { return (bf16_t*)(ws + OFF_Z); }
; DI float bflo(unsigned u) { return __uint_as_float(u << 16); }
; DI float bfhi(unsigned u) { return __uint_as_float(u & 0xffff0000u); }
; DI void row_rstd(const bf16_t* __restrict__ A, int lda, int K, int m0, float* rs) {
;     ...
;   for (int c = 0; c < K / 2; c += 8) {
;     const u32x4 v = *(const u32x4*)(r + c);
;     ss += bflo(v.x) * bflo(v.x) + bfhi(v.x) * bfhi(v.x) + bflo(v.y) * bflo(v.y) + bfhi(v.y) * bfhi(v.y) +
;           bflo(v.z) * bflo(v.z) + bfhi(v.z) * bfhi(v.z) + bflo(v.w) * bflo(v.w) + bfhi(v.w) * bfhi(v.w);
;   }
	v_lshlrev_b32_e32 v22, 16, v76
	v_and_b32_e32 v23, 0xffff0000, v76
	v_pk_mul_f32 v[22:23], v[22:23], v[22:23]
	v_and_b32_e32 v76, 0xffff0000, v77
	v_lshlrev_b32_e32 v77, 16, v77
	v_pk_mul_f32 v[76:77], v[76:77], v[76:77]
	v_add_f32_e32 v5, v22, v23
	v_and_b32_e32 v24, 0xffff0000, v78
	v_lshlrev_b32_e32 v25, 16, v78
	v_add_f32_e32 v5, v77, v5
	v_pk_mul_f32 v[24:25], v[24:25], v[24:25]
	v_add_f32_e32 v5, v76, v5
	v_and_b32_e32 v78, 0xffff0000, v79
	v_lshlrev_b32_e32 v79, 16, v79
	v_add_f32_e32 v5, v25, v5
	v_pk_mul_f32 v[78:79], v[78:79], v[78:79]
	v_add_f32_e32 v5, v24, v5
	v_add_f32_e32 v5, v79, v5
	v_add_f32_e32 v5, v78, v5
	v_add_f32_e32 v78, v4, v5
	v_lshlrev_b32_e32 v4, 16, v72
	v_and_b32_e32 v5, 0xffff0000, v72
	v_pk_mul_f32 v[4:5], v[4:5], v[4:5]
	v_and_b32_e32 v72, 0xffff0000, v73
	v_lshlrev_b32_e32 v73, 16, v73
	v_pk_mul_f32 v[72:73], v[72:73], v[72:73]
	v_add_f32_e32 v4, v4, v5
	v_and_b32_e32 v76, 0xffff0000, v74
	v_lshlrev_b32_e32 v77, 16, v74
	v_add_f32_e32 v4, v73, v4
	v_pk_mul_f32 v[76:77], v[76:77], v[76:77]
	v_add_f32_e32 v4, v72, v4
	v_and_b32_e32 v74, 0xffff0000, v75
	v_lshlrev_b32_e32 v75, 16, v75
	v_add_f32_e32 v4, v77, v4
	v_pk_mul_f32 v[74:75], v[74:75], v[74:75]
	v_add_f32_e32 v4, v76, v4
	v_add_f32_e32 v4, v75, v4
	v_add_f32_e32 v4, v74, v4
	v_add_f32_e32 v74, v78, v4
	v_lshlrev_b32_e32 v4, 16, v68
	v_and_b32_e32 v5, 0xffff0000, v68
	v_pk_mul_f32 v[4:5], v[4:5], v[4:5]
	v_and_b32_e32 v68, 0xffff0000, v69
	v_lshlrev_b32_e32 v69, 16, v69
	v_pk_mul_f32 v[68:69], v[68:69], v[68:69]
	v_add_f32_e32 v4, v4, v5
	v_and_b32_e32 v72, 0xffff0000, v70
	v_lshlrev_b32_e32 v73, 16, v70
	v_add_f32_e32 v4, v69, v4
	v_pk_mul_f32 v[72:73], v[72:73], v[72:73]
	v_add_f32_e32 v4, v68, v4
	v_and_b32_e32 v70, 0xffff0000, v71
	v_lshlrev_b32_e32 v71, 16, v71
	v_add_f32_e32 v4, v73, v4
	v_pk_mul_f32 v[70:71], v[70:71], v[70:71]
	v_add_f32_e32 v4, v72, v4
	v_add_f32_e32 v4, v71, v4
	v_add_f32_e32 v4, v70, v4
	v_add_f32_e32 v70, v74, v4
	v_lshlrev_b32_e32 v4, 16, v64
	v_and_b32_e32 v5, 0xffff0000, v64
	v_pk_mul_f32 v[4:5], v[4:5], v[4:5]
	v_and_b32_e32 v64, 0xffff0000, v65
	v_lshlrev_b32_e32 v65, 16, v65
	v_pk_mul_f32 v[64:65], v[64:65], v[64:65]
	v_add_f32_e32 v4, v4, v5
	v_and_b32_e32 v68, 0xffff0000, v66
	v_lshlrev_b32_e32 v69, 16, v66
	v_add_f32_e32 v4, v65, v4
	v_pk_mul_f32 v[68:69], v[68:69], v[68:69]
	v_add_f32_e32 v4, v64, v4
	v_and_b32_e32 v66, 0xffff0000, v67
	v_lshlrev_b32_e32 v67, 16, v67
	v_add_f32_e32 v4, v69, v4
	v_pk_mul_f32 v[66:67], v[66:67], v[66:67]
	v_add_f32_e32 v4, v68, v4
	v_add_f32_e32 v4, v67, v4
	v_add_f32_e32 v4, v66, v4
	v_add_f32_e32 v4, v70, v4
	s_waitcnt vmcnt(0)
	v_lshlrev_b32_e32 v22, 16, v92
	v_and_b32_e32 v23, 0xffff0000, v92
	v_pk_mul_f32 v[22:23], v[22:23], v[22:23]
	v_and_b32_e32 v92, 0xffff0000, v93
	v_lshlrev_b32_e32 v93, 16, v93
	v_pk_mul_f32 v[92:93], v[92:93], v[92:93]
	v_add_f32_e32 v5, v22, v23
	v_and_b32_e32 v24, 0xffff0000, v94
	v_lshlrev_b32_e32 v25, 16, v94
	v_add_f32_e32 v5, v93, v5
	v_pk_mul_f32 v[24:25], v[24:25], v[24:25]
	v_add_f32_e32 v5, v92, v5
	v_and_b32_e32 v94, 0xffff0000, v95
	v_lshlrev_b32_e32 v95, 16, v95
	v_add_f32_e32 v5, v25, v5
	v_pk_mul_f32 v[94:95], v[94:95], v[94:95]
	v_add_f32_e32 v5, v24, v5
	v_add_f32_e32 v5, v95, v5
	v_add_f32_e32 v5, v94, v5
	v_add_f32_e32 v94, v4, v5
	v_lshlrev_b32_e32 v4, 16, v88
	v_and_b32_e32 v5, 0xffff0000, v88
	v_pk_mul_f32 v[4:5], v[4:5], v[4:5]
	v_and_b32_e32 v88, 0xffff0000, v89
	v_lshlrev_b32_e32 v89, 16, v89
	v_pk_mul_f32 v[88:89], v[88:89], v[88:89]
	v_add_f32_e32 v4, v4, v5
	v_and_b32_e32 v92, 0xffff0000, v90
	v_lshlrev_b32_e32 v93, 16, v90
	v_add_f32_e32 v4, v89, v4
	v_pk_mul_f32 v[92:93], v[92:93], v[92:93]
	v_add_f32_e32 v4, v88, v4
	v_and_b32_e32 v90, 0xffff0000, v91
	v_lshlrev_b32_e32 v91, 16, v91
	v_add_f32_e32 v4, v93, v4
	v_pk_mul_f32 v[90:91], v[90:91], v[90:91]
	v_add_f32_e32 v4, v92, v4
	v_add_f32_e32 v4, v91, v4
	v_add_f32_e32 v4, v90, v4
	v_add_f32_e32 v90, v94, v4
	v_lshlrev_b32_e32 v4, 16, v84
	v_and_b32_e32 v5, 0xffff0000, v84
	v_pk_mul_f32 v[4:5], v[4:5], v[4:5]
	v_and_b32_e32 v84, 0xffff0000, v85
	v_lshlrev_b32_e32 v85, 16, v85
	v_pk_mul_f32 v[84:85], v[84:85], v[84:85]
	v_add_f32_e32 v4, v4, v5
	v_and_b32_e32 v88, 0xffff0000, v86
	v_lshlrev_b32_e32 v89, 16, v86
	v_add_f32_e32 v4, v85, v4
	v_pk_mul_f32 v[88:89], v[88:89], v[88:89]
	v_add_f32_e32 v4, v84, v4
	v_and_b32_e32 v86, 0xffff0000, v87
	v_lshlrev_b32_e32 v87, 16, v87
	v_add_f32_e32 v4, v89, v4
	v_pk_mul_f32 v[86:87], v[86:87], v[86:87]
	v_add_f32_e32 v4, v88, v4
	v_add_f32_e32 v4, v87, v4
	v_add_f32_e32 v4, v86, v4
	v_add_f32_e32 v86, v90, v4
	v_lshlrev_b32_e32 v4, 16, v80
	v_and_b32_e32 v5, 0xffff0000, v80
	v_pk_mul_f32 v[4:5], v[4:5], v[4:5]
	v_and_b32_e32 v80, 0xffff0000, v81
	v_lshlrev_b32_e32 v81, 16, v81
	v_pk_mul_f32 v[80:81], v[80:81], v[80:81]
	v_add_f32_e32 v4, v4, v5
	v_and_b32_e32 v84, 0xffff0000, v82
	v_lshlrev_b32_e32 v85, 16, v82
	v_add_f32_e32 v4, v81, v4
	v_pk_mul_f32 v[84:85], v[84:85], v[84:85]
	v_add_f32_e32 v4, v80, v4
	v_and_b32_e32 v82, 0xffff0000, v83
	v_lshlrev_b32_e32 v83, 16, v83
	v_add_f32_e32 v4, v85, v4
	v_pk_mul_f32 v[82:83], v[82:83], v[82:83]
	v_add_f32_e32 v4, v84, v4
	v_add_f32_e32 v4, v83, v4
	v_add_f32_e32 v4, v82, v4
	v_add_f32_e32 v4, v86, v4
	global_load_dwordx4 v[44:47], v[0:1], off offset:224
	global_load_dwordx4 v[40:43], v[0:1], off offset:240
	global_load_dwordx4 v[36:39], v[0:1], off offset:256
	global_load_dwordx4 v[32:35], v[0:1], off offset:272
	global_load_dwordx4 v[60:63], v[0:1], off offset:288
	global_load_dwordx4 v[56:59], v[0:1], off offset:304
	global_load_dwordx4 v[52:55], v[0:1], off offset:320
	global_load_dwordx4 v[48:51], v[0:1], off offset:336
	global_load_dwordx4 v[76:79], v[0:1], off offset:352
	global_load_dwordx4 v[72:75], v[0:1], off offset:368
	global_load_dwordx4 v[68:71], v[0:1], off offset:384
	global_load_dwordx4 v[64:67], v[0:1], off offset:400
	global_load_dwordx4 v[92:95], v[0:1], off offset:416
	global_load_dwordx4 v[88:91], v[0:1], off offset:432
	global_load_dwordx4 v[84:87], v[0:1], off offset:448
	global_load_dwordx4 v[80:83], v[0:1], off offset:464
	s_waitcnt vmcnt(12)
;   DI bf16_t* z() const { return (bf16_t*)(ws + OFF_Z); }
; DI float bflo(unsigned u) { return __uint_as_float(u << 16); }
; DI float bfhi(unsigned u) { return __uint_as_float(u & 0xffff0000u); }
; DI void row_rstd(const bf16_t* __restrict__ A, int lda, int K, int m0, float* rs) {
;     ...
;   for (int c = 0; c < K / 2; c += 8) {
;     const u32x4 v = *(const u32x4*)(r + c);
;     ss += bflo(v.x) * bflo(v.x) + bfhi(v.x) * bfhi(v.x) + bflo(v.y) * bflo(v.y) + bfhi(v.y) * bfhi(v.y) +
;           bflo(v.z) * bflo(v.z) + bfhi(v.z) * bfhi(v.z) + bflo(v.w) * bflo(v.w) + bfhi(v.w) * bfhi(v.w);
;   }
	v_lshlrev_b32_e32 v22, 16, v44
	v_and_b32_e32 v23, 0xffff0000, v44
	v_pk_mul_f32 v[22:23], v[22:23], v[22:23]
	v_and_b32_e32 v44, 0xffff0000, v45
	v_lshlrev_b32_e32 v45, 16, v45
	v_pk_mul_f32 v[44:45], v[44:45], v[44:45]
	v_add_f32_e32 v5, v22, v23
	v_and_b32_e32 v24, 0xffff0000, v46
	v_lshlrev_b32_e32 v25, 16, v46
	v_add_f32_e32 v5, v45, v5
	v_pk_mul_f32 v[24:25], v[24:25], v[24:25]
	v_add_f32_e32 v5, v44, v5
	v_and_b32_e32 v46, 0xffff0000, v47
	v_lshlrev_b32_e32 v47, 16, v47
	v_add_f32_e32 v5, v25, v5
	v_pk_mul_f32 v[46:47], v[46:47], v[46:47]
	v_add_f32_e32 v5, v24, v5
	v_add_f32_e32 v5, v47, v5
	v_add_f32_e32 v5, v46, v5
	v_add_f32_e32 v46, v4, v5
	v_lshlrev_b32_e32 v4, 16, v40
	v_and_b32_e32 v5, 0xffff0000, v40
	v_pk_mul_f32 v[4:5], v[4:5], v[4:5]
	v_and_b32_e32 v40, 0xffff0000, v41
	v_lshlrev_b32_e32 v41, 16, v41
	v_pk_mul_f32 v[40:41], v[40:41], v[40:41]
	v_add_f32_e32 v4, v4, v5
	v_and_b32_e32 v44, 0xffff0000, v42
	v_lshlrev_b32_e32 v45, 16, v42
	v_add_f32_e32 v4, v41, v4
	v_pk_mul_f32 v[44:45], v[44:45], v[44:45]
	v_add_f32_e32 v4, v40, v4
	v_and_b32_e32 v42, 0xffff0000, v43
	v_lshlrev_b32_e32 v43, 16, v43
	v_add_f32_e32 v4, v45, v4
	v_pk_mul_f32 v[42:43], v[42:43], v[42:43]
	v_add_f32_e32 v4, v44, v4
	v_add_f32_e32 v4, v43, v4
	v_add_f32_e32 v4, v42, v4
	v_add_f32_e32 v42, v46, v4
	v_lshlrev_b32_e32 v4, 16, v36
	v_and_b32_e32 v5, 0xffff0000, v36
	v_pk_mul_f32 v[4:5], v[4:5], v[4:5]
	v_and_b32_e32 v36, 0xffff0000, v37
	v_lshlrev_b32_e32 v37, 16, v37
	v_pk_mul_f32 v[36:37], v[36:37], v[36:37]
	v_add_f32_e32 v4, v4, v5
	v_and_b32_e32 v40, 0xffff0000, v38
	v_lshlrev_b32_e32 v41, 16, v38
	v_add_f32_e32 v4, v37, v4
	v_pk_mul_f32 v[40:41], v[40:41], v[40:41]
	v_add_f32_e32 v4, v36, v4
	v_and_b32_e32 v38, 0xffff0000, v39
	v_lshlrev_b32_e32 v39, 16, v39
	v_add_f32_e32 v4, v41, v4
	v_pk_mul_f32 v[38:39], v[38:39], v[38:39]
	v_add_f32_e32 v4, v40, v4
	v_add_f32_e32 v4, v39, v4
	v_add_f32_e32 v4, v38, v4
	v_add_f32_e32 v38, v42, v4
	v_lshlrev_b32_e32 v4, 16, v32
	v_and_b32_e32 v5, 0xffff0000, v32
	v_pk_mul_f32 v[4:5], v[4:5], v[4:5]
	v_and_b32_e32 v32, 0xffff0000, v33
	v_lshlrev_b32_e32 v33, 16, v33
	v_pk_mul_f32 v[32:33], v[32:33], v[32:33]
	v_add_f32_e32 v4, v4, v5
	v_and_b32_e32 v36, 0xffff0000, v34
	v_lshlrev_b32_e32 v37, 16, v34
	v_add_f32_e32 v4, v33, v4
	v_pk_mul_f32 v[36:37], v[36:37], v[36:37]
	v_add_f32_e32 v4, v32, v4
	v_and_b32_e32 v34, 0xffff0000, v35
	v_lshlrev_b32_e32 v35, 16, v35
	v_add_f32_e32 v4, v37, v4
	v_pk_mul_f32 v[34:35], v[34:35], v[34:35]
	v_add_f32_e32 v4, v36, v4
	v_add_f32_e32 v4, v35, v4
	v_add_f32_e32 v4, v34, v4
	v_add_f32_e32 v4, v38, v4
	s_waitcnt vmcnt(8)
	v_lshlrev_b32_e32 v22, 16, v60
	v_and_b32_e32 v23, 0xffff0000, v60
	v_pk_mul_f32 v[22:23], v[22:23], v[22:23]
	v_and_b32_e32 v60, 0xffff0000, v61
	v_lshlrev_b32_e32 v61, 16, v61
	v_pk_mul_f32 v[60:61], v[60:61], v[60:61]
	v_add_f32_e32 v5, v22, v23
	v_and_b32_e32 v24, 0xffff0000, v62
	v_lshlrev_b32_e32 v25, 16, v62
	v_add_f32_e32 v5, v61, v5
	v_pk_mul_f32 v[24:25], v[24:25], v[24:25]
	v_add_f32_e32 v5, v60, v5
	v_and_b32_e32 v62, 0xffff0000, v63
	v_lshlrev_b32_e32 v63, 16, v63
	v_add_f32_e32 v5, v25, v5
	v_pk_mul_f32 v[62:63], v[62:63], v[62:63]
	v_add_f32_e32 v5, v24, v5
	v_add_f32_e32 v5, v63, v5
	v_add_f32_e32 v5, v62, v5
	v_add_f32_e32 v62, v4, v5
	v_lshlrev_b32_e32 v4, 16, v56
	v_and_b32_e32 v5, 0xffff0000, v56
	v_pk_mul_f32 v[4:5], v[4:5], v[4:5]
	v_and_b32_e32 v56, 0xffff0000, v57
	v_lshlrev_b32_e32 v57, 16, v57
	v_pk_mul_f32 v[56:57], v[56:57], v[56:57]
	v_add_f32_e32 v4, v4, v5
	v_and_b32_e32 v60, 0xffff0000, v58
	v_lshlrev_b32_e32 v61, 16, v58
	v_add_f32_e32 v4, v57, v4
	v_pk_mul_f32 v[60:61], v[60:61], v[60:61]
	v_add_f32_e32 v4, v56, v4
	v_and_b32_e32 v58, 0xffff0000, v59
	v_lshlrev_b32_e32 v59, 16, v59
	v_add_f32_e32 v4, v61, v4
	v_pk_mul_f32 v[58:59], v[58:59], v[58:59]
	v_add_f32_e32 v4, v60, v4
	v_add_f32_e32 v4, v59, v4
	v_add_f32_e32 v4, v58, v4
	v_add_f32_e32 v58, v62, v4
	v_lshlrev_b32_e32 v4, 16, v52
	v_and_b32_e32 v5, 0xffff0000, v52
	v_pk_mul_f32 v[4:5], v[4:5], v[4:5]
	v_and_b32_e32 v52, 0xffff0000, v53
	v_lshlrev_b32_e32 v53, 16, v53
	v_pk_mul_f32 v[52:53], v[52:53], v[52:53]
	v_add_f32_e32 v4, v4, v5
	v_and_b32_e32 v56, 0xffff0000, v54
	v_lshlrev_b32_e32 v57, 16, v54
	v_add_f32_e32 v4, v53, v4
	v_pk_mul_f32 v[56:57], v[56:57], v[56:57]
	v_add_f32_e32 v4, v52, v4
	v_and_b32_e32 v54, 0xffff0000, v55
	v_lshlrev_b32_e32 v55, 16, v55
	v_add_f32_e32 v4, v57, v4
	v_pk_mul_f32 v[54:55], v[54:55], v[54:55]
	v_add_f32_e32 v4, v56, v4
	v_add_f32_e32 v4, v55, v4
	v_add_f32_e32 v4, v54, v4
	v_add_f32_e32 v54, v58, v4
	v_lshlrev_b32_e32 v4, 16, v48
	v_and_b32_e32 v5, 0xffff0000, v48
	v_pk_mul_f32 v[4:5], v[4:5], v[4:5]
	v_and_b32_e32 v48, 0xffff0000, v49
	v_lshlrev_b32_e32 v49, 16, v49
	v_pk_mul_f32 v[48:49], v[48:49], v[48:49]
	v_add_f32_e32 v4, v4, v5
	v_and_b32_e32 v52, 0xffff0000, v50
	v_lshlrev_b32_e32 v53, 16, v50
	v_add_f32_e32 v4, v49, v4
	v_pk_mul_f32 v[52:53], v[52:53], v[52:53]
	v_add_f32_e32 v4, v48, v4
	v_and_b32_e32 v50, 0xffff0000, v51
	v_lshlrev_b32_e32 v51, 16, v51
	v_add_f32_e32 v4, v53, v4
	v_pk_mul_f32 v[50:51], v[50:51], v[50:51]
	v_add_f32_e32 v4, v52, v4
	v_add_f32_e32 v4, v51, v4
	v_add_f32_e32 v4, v50, v4
	v_add_f32_e32 v4, v54, v4
	s_waitcnt vmcnt(4)
;   DI bf16_t* z() const { return (bf16_t*)(ws + OFF_Z); }
; DI float bflo(unsigned u) { return __uint_as_float(u << 16); }
; DI float bfhi(unsigned u) { return __uint_as_float(u & 0xffff0000u); }
; DI void row_rstd(const bf16_t* __restrict__ A, int lda, int K, int m0, float* rs) {
;     ...
;   for (int c = 0; c < K / 2; c += 8) {
;     const u32x4 v = *(const u32x4*)(r + c);
;     ss += bflo(v.x) * bflo(v.x) + bfhi(v.x) * bfhi(v.x) + bflo(v.y) * bflo(v.y) + bfhi(v.y) * bfhi(v.y) +
;           bflo(v.z) * bflo(v.z) + bfhi(v.z) * bfhi(v.z) + bflo(v.w) * bflo(v.w) + bfhi(v.w) * bfhi(v.w);
;   }
;   ss += __shfl_xor(ss, 1);
;   if ((tid & 1) == 0) rs[tid >> 1] = rsqrtf(ss / (float)K + EPS);
;   __syncthreads();
	v_lshlrev_b32_e32 v22, 16, v76
	v_and_b32_e32 v23, 0xffff0000, v76
	v_pk_mul_f32 v[22:23], v[22:23], v[22:23]
	v_and_b32_e32 v76, 0xffff0000, v77
	v_lshlrev_b32_e32 v77, 16, v77
	v_pk_mul_f32 v[76:77], v[76:77], v[76:77]
	v_add_f32_e32 v5, v22, v23
	v_and_b32_e32 v24, 0xffff0000, v78
	v_lshlrev_b32_e32 v25, 16, v78
	v_add_f32_e32 v5, v77, v5
	v_pk_mul_f32 v[24:25], v[24:25], v[24:25]
	v_add_f32_e32 v5, v76, v5
	v_and_b32_e32 v78, 0xffff0000, v79
	v_lshlrev_b32_e32 v79, 16, v79
	v_add_f32_e32 v5, v25, v5
	v_pk_mul_f32 v[78:79], v[78:79], v[78:79]
	v_add_f32_e32 v5, v24, v5
	v_add_f32_e32 v5, v79, v5
	v_add_f32_e32 v5, v78, v5
	v_add_f32_e32 v78, v4, v5
	v_lshlrev_b32_e32 v4, 16, v72
	v_and_b32_e32 v5, 0xffff0000, v72
	v_pk_mul_f32 v[4:5], v[4:5], v[4:5]
	v_and_b32_e32 v72, 0xffff0000, v73
	v_lshlrev_b32_e32 v73, 16, v73
	v_pk_mul_f32 v[72:73], v[72:73], v[72:73]
	v_add_f32_e32 v4, v4, v5
	v_and_b32_e32 v76, 0xffff0000, v74
	v_lshlrev_b32_e32 v77, 16, v74
	v_add_f32_e32 v4, v73, v4
	v_pk_mul_f32 v[76:77], v[76:77], v[76:77]
	v_add_f32_e32 v4, v72, v4
	v_and_b32_e32 v74, 0xffff0000, v75
	v_lshlrev_b32_e32 v75, 16, v75
	v_add_f32_e32 v4, v77, v4
	v_pk_mul_f32 v[74:75], v[74:75], v[74:75]
	v_add_f32_e32 v4, v76, v4
	v_add_f32_e32 v4, v75, v4
	v_add_f32_e32 v4, v74, v4
	v_add_f32_e32 v74, v78, v4
	v_lshlrev_b32_e32 v4, 16, v68
	v_and_b32_e32 v5, 0xffff0000, v68
	v_pk_mul_f32 v[4:5], v[4:5], v[4:5]
	v_and_b32_e32 v68, 0xffff0000, v69
	v_lshlrev_b32_e32 v69, 16, v69
	v_pk_mul_f32 v[68:69], v[68:69], v[68:69]
	v_add_f32_e32 v4, v4, v5
	v_and_b32_e32 v72, 0xffff0000, v70
	v_lshlrev_b32_e32 v73, 16, v70
	v_add_f32_e32 v4, v69, v4
	v_pk_mul_f32 v[72:73], v[72:73], v[72:73]
	v_add_f32_e32 v4, v68, v4
	v_and_b32_e32 v70, 0xffff0000, v71
	v_lshlrev_b32_e32 v71, 16, v71
	v_add_f32_e32 v4, v73, v4
	v_pk_mul_f32 v[70:71], v[70:71], v[70:71]
	v_add_f32_e32 v4, v72, v4
	v_add_f32_e32 v4, v71, v4
	v_add_f32_e32 v4, v70, v4
	v_add_f32_e32 v70, v74, v4
	v_lshlrev_b32_e32 v4, 16, v64
	v_and_b32_e32 v5, 0xffff0000, v64
	v_pk_mul_f32 v[4:5], v[4:5], v[4:5]
	v_and_b32_e32 v64, 0xffff0000, v65
	v_lshlrev_b32_e32 v65, 16, v65
	v_pk_mul_f32 v[64:65], v[64:65], v[64:65]
	v_add_f32_e32 v4, v4, v5
	v_and_b32_e32 v68, 0xffff0000, v66
	v_lshlrev_b32_e32 v69, 16, v66
	v_add_f32_e32 v4, v65, v4
	v_pk_mul_f32 v[68:69], v[68:69], v[68:69]
	v_add_f32_e32 v4, v64, v4
	v_and_b32_e32 v66, 0xffff0000, v67
	v_lshlrev_b32_e32 v67, 16, v67
	v_add_f32_e32 v4, v69, v4
	v_pk_mul_f32 v[66:67], v[66:67], v[66:67]
	v_add_f32_e32 v4, v68, v4
	v_add_f32_e32 v4, v67, v4
	v_add_f32_e32 v4, v66, v4
	v_add_f32_e32 v4, v70, v4
	s_waitcnt vmcnt(0)
	v_lshlrev_b32_e32 v22, 16, v92
	v_and_b32_e32 v23, 0xffff0000, v92
	v_pk_mul_f32 v[22:23], v[22:23], v[22:23]
	v_and_b32_e32 v92, 0xffff0000, v93
	v_lshlrev_b32_e32 v93, 16, v93
	v_pk_mul_f32 v[92:93], v[92:93], v[92:93]
	v_add_f32_e32 v5, v22, v23
	v_and_b32_e32 v24, 0xffff0000, v94
	v_lshlrev_b32_e32 v25, 16, v94
	v_add_f32_e32 v5, v93, v5
	v_pk_mul_f32 v[24:25], v[24:25], v[24:25]
	v_add_f32_e32 v5, v92, v5
	v_and_b32_e32 v94, 0xffff0000, v95
	v_lshlrev_b32_e32 v95, 16, v95
	v_add_f32_e32 v5, v25, v5
	v_pk_mul_f32 v[94:95], v[94:95], v[94:95]
	v_add_f32_e32 v5, v24, v5
	v_add_f32_e32 v5, v95, v5
	v_add_f32_e32 v5, v94, v5
	v_add_f32_e32 v94, v4, v5
	v_lshlrev_b32_e32 v4, 16, v88
	v_and_b32_e32 v5, 0xffff0000, v88
	v_pk_mul_f32 v[4:5], v[4:5], v[4:5]
	v_and_b32_e32 v88, 0xffff0000, v89
	v_lshlrev_b32_e32 v89, 16, v89
	v_pk_mul_f32 v[88:89], v[88:89], v[88:89]
	v_add_f32_e32 v4, v4, v5
	v_and_b32_e32 v92, 0xffff0000, v90
	v_lshlrev_b32_e32 v93, 16, v90
	v_add_f32_e32 v4, v89, v4
	v_pk_mul_f32 v[92:93], v[92:93], v[92:93]
	v_add_f32_e32 v4, v88, v4
	v_and_b32_e32 v90, 0xffff0000, v91
	v_lshlrev_b32_e32 v91, 16, v91
	v_add_f32_e32 v4, v93, v4
	v_pk_mul_f32 v[90:91], v[90:91], v[90:91]
	v_add_f32_e32 v4, v92, v4
	v_add_f32_e32 v4, v91, v4
	v_add_f32_e32 v4, v90, v4
	v_add_f32_e32 v90, v94, v4
	v_lshlrev_b32_e32 v4, 16, v84
	v_and_b32_e32 v5, 0xffff0000, v84
	v_pk_mul_f32 v[4:5], v[4:5], v[4:5]
	v_and_b32_e32 v84, 0xffff0000, v85
	v_lshlrev_b32_e32 v85, 16, v85
	v_pk_mul_f32 v[84:85], v[84:85], v[84:85]
	v_add_f32_e32 v4, v4, v5
	v_and_b32_e32 v88, 0xffff0000, v86
	v_lshlrev_b32_e32 v89, 16, v86
	v_add_f32_e32 v4, v85, v4
	v_pk_mul_f32 v[88:89], v[88:89], v[88:89]
	v_add_f32_e32 v4, v84, v4
	v_and_b32_e32 v86, 0xffff0000, v87
	v_lshlrev_b32_e32 v87, 16, v87
	v_add_f32_e32 v4, v89, v4
	v_pk_mul_f32 v[86:87], v[86:87], v[86:87]
	v_add_f32_e32 v4, v88, v4
	v_add_f32_e32 v4, v87, v4
	v_add_f32_e32 v4, v86, v4
	v_add_f32_e32 v86, v90, v4
	v_lshlrev_b32_e32 v4, 16, v80
	v_and_b32_e32 v5, 0xffff0000, v80
	v_pk_mul_f32 v[4:5], v[4:5], v[4:5]
	v_and_b32_e32 v80, 0xffff0000, v81
	v_lshlrev_b32_e32 v81, 16, v81
	v_pk_mul_f32 v[80:81], v[80:81], v[80:81]
	v_add_f32_e32 v4, v4, v5
	v_and_b32_e32 v84, 0xffff0000, v82
	v_lshlrev_b32_e32 v85, 16, v82
	v_add_f32_e32 v4, v81, v4
	v_pk_mul_f32 v[84:85], v[84:85], v[84:85]
	v_add_f32_e32 v4, v80, v4
	v_and_b32_e32 v82, 0xffff0000, v83
	v_lshlrev_b32_e32 v83, 16, v83
	v_add_f32_e32 v4, v85, v4
	v_pk_mul_f32 v[82:83], v[82:83], v[82:83]
	v_add_f32_e32 v4, v84, v4
	v_add_f32_e32 v4, v83, v4
	v_add_f32_e32 v4, v82, v4
	v_add_f32_e32 v4, v86, v4
	v_and_b32_e32 v1, 64, v209
	v_xor_b32_e32 v0, 1, v209
	v_add_u32_e32 v1, 64, v1
	v_cmp_lt_i32_e32 vcc, v0, v1
	s_nop 1
	v_cndmask_b32_e32 v0, v209, v0, vcc
	v_lshlrev_b32_e32 v0, 2, v0
	ds_bpermute_b32 v0, v0, v4
	v_cmp_eq_u32_e32 vcc, 0, v3
	s_and_saveexec_b64 s[2:3], vcc
	s_cbranch_execz .LBB0_983
	s_waitcnt lgkmcnt(0)
	v_add_f32_e32 v0, v4, v0
	v_fmamk_f32 v0, v0, 0x3b000000, v208
	v_mul_f32_e32 v1, 0x4b800000, v0
	v_cmp_gt_f32_e32 vcc, s33, v0
	s_nop 1
	v_cndmask_b32_e32 v0, v0, v1, vcc
	v_rsq_f32_e32 v0, v0
	v_lshl_add_u32 v1, v2, 2, 16
	v_add_u32_e32 v1, 0x24000, v1
	v_mul_f32_e32 v2, 0x45800000, v0
	v_cndmask_b32_e32 v0, v0, v2, vcc
	ds_write_b32 v1, v0

;   DI bf16_t* z() const { return (bf16_t*)(ws + OFF_Z); }
; DI float bflo(unsigned u) { return __uint_as_float(u << 16); }
; DI float bfhi(unsigned u) { return __uint_as_float(u & 0xffff0000u); }
; DI int otid() { int t = threadIdx.x; asm volatile("" : "+v"(t)); return t; }
; DI void row_rstd(const bf16_t* __restrict__ A, int lda, int K, int m0, float* rs) {
;   const int tid = otid();
;   const bf16_t* r = A + (size_t)(m0 + (tid >> 1)) * lda + (tid & 1) * (K / 2);
;   float ss = 0.f;
;   for (int c = 0; c < K / 2; c += 8) {
;     const u32x4 v = *(const u32x4*)(r + c);
;     ss += bflo(v.x) * bflo(v.x) + bfhi(v.x) * bfhi(v.x) + bflo(v.y) * bflo(v.y) + bfhi(v.y) * bfhi(v.y) +
;           bflo(v.z) * bflo(v.z) + bfhi(v.z) * bfhi(v.z) + bflo(v.w) * bflo(v.w) + bfhi(v.w) * bfhi(v.w);
;   }
.LBB0_1024:
	global_load_dwordx4 v[44:47], v[0:1], off offset:-32
	global_load_dwordx4 v[40:43], v[0:1], off offset:-16
	global_load_dwordx4 v[36:39], v[0:1], off
	global_load_dwordx4 v[32:35], v[0:1], off offset:16
	global_load_dwordx4 v[60:63], v[0:1], off offset:32
	global_load_dwordx4 v[56:59], v[0:1], off offset:48
	global_load_dwordx4 v[52:55], v[0:1], off offset:64
	global_load_dwordx4 v[48:51], v[0:1], off offset:80
	global_load_dwordx4 v[76:79], v[0:1], off offset:96
	global_load_dwordx4 v[72:75], v[0:1], off offset:112
	global_load_dwordx4 v[68:71], v[0:1], off offset:128
	global_load_dwordx4 v[64:67], v[0:1], off offset:144
	global_load_dwordx4 v[92:95], v[0:1], off offset:160
	global_load_dwordx4 v[88:91], v[0:1], off offset:176
	global_load_dwordx4 v[84:87], v[0:1], off offset:192
	global_load_dwordx4 v[80:83], v[0:1], off offset:208
	s_waitcnt vmcnt(12)
	v_lshlrev_b32_e32 v22, 16, v44
	v_and_b32_e32 v23, 0xffff0000, v44
	v_pk_mul_f32 v[22:23], v[22:23], v[22:23]
	v_and_b32_e32 v44, 0xffff0000, v45
	v_lshlrev_b32_e32 v45, 16, v45
	v_pk_mul_f32 v[44:45], v[44:45], v[44:45]
	v_add_f32_e32 v5, v22, v23
	v_and_b32_e32 v24, 0xffff0000, v46
	v_lshlrev_b32_e32 v25, 16, v46
	v_add_f32_e32 v5, v45, v5
	v_pk_mul_f32 v[24:25], v[24:25], v[24:25]
	v_add_f32_e32 v5, v44, v5
	v_and_b32_e32 v46, 0xffff0000, v47
	v_lshlrev_b32_e32 v47, 16, v47
	v_add_f32_e32 v5, v25, v5
	v_pk_mul_f32 v[46:47], v[46:47], v[46:47]
	v_add_f32_e32 v5, v24, v5
	v_add_f32_e32 v5, v47, v5
	v_add_f32_e32 v5, v46, v5
	v_add_f32_e32 v46, v4, v5
	v_lshlrev_b32_e32 v4, 16, v40
	v_and_b32_e32 v5, 0xffff0000, v40
	v_pk_mul_f32 v[4:5], v[4:5], v[4:5]
	v_and_b32_e32 v40, 0xffff0000, v41
	v_lshlrev_b32_e32 v41, 16, v41
	v_pk_mul_f32 v[40:41], v[40:41], v[40:41]
	v_add_f32_e32 v4, v4, v5
	v_and_b32_e32 v44, 0xffff0000, v42
	v_lshlrev_b32_e32 v45, 16, v42
	v_add_f32_e32 v4, v41, v4
	v_pk_mul_f32 v[44:45], v[44:45], v[44:45]
	v_add_f32_e32 v4, v40, v4
	v_and_b32_e32 v42, 0xffff0000, v43
	v_lshlrev_b32_e32 v43, 16, v43
	v_add_f32_e32 v4, v45, v4
	v_pk_mul_f32 v[42:43], v[42:43], v[42:43]
	v_add_f32_e32 v4, v44, v4
	v_add_f32_e32 v4, v43, v4
	v_add_f32_e32 v4, v42, v4
	v_add_f32_e32 v42, v46, v4
	v_lshlrev_b32_e32 v4, 16, v36
	v_and_b32_e32 v5, 0xffff0000, v36
	v_pk_mul_f32 v[4:5], v[4:5], v[4:5]
	v_and_b32_e32 v36, 0xffff0000, v37
	v_lshlrev_b32_e32 v37, 16, v37
	v_pk_mul_f32 v[36:37], v[36:37], v[36:37]
	v_add_f32_e32 v4, v4, v5
	v_and_b32_e32 v40, 0xffff0000, v38
	v_lshlrev_b32_e32 v41, 16, v38
	v_add_f32_e32 v4, v37, v4
	v_pk_mul_f32 v[40:41], v[40:41], v[40:41]
	v_add_f32_e32 v4, v36, v4
	v_and_b32_e32 v38, 0xffff0000, v39
	v_lshlrev_b32_e32 v39, 16, v39
	v_add_f32_e32 v4, v41, v4
	v_pk_mul_f32 v[38:39], v[38:39], v[38:39]
	v_add_f32_e32 v4, v40, v4
	v_add_f32_e32 v4, v39, v4
	v_add_f32_e32 v4, v38, v4
	v_add_f32_e32 v38, v42, v4
	v_lshlrev_b32_e32 v4, 16, v32
	v_and_b32_e32 v5, 0xffff0000, v32
	v_pk_mul_f32 v[4:5], v[4:5], v[4:5]
	v_and_b32_e32 v32, 0xffff0000, v33
	v_lshlrev_b32_e32 v33, 16, v33
	v_pk_mul_f32 v[32:33], v[32:33], v[32:33]
	v_add_f32_e32 v4, v4, v5
	v_and_b32_e32 v36, 0xffff0000, v34
	v_lshlrev_b32_e32 v37, 16, v34
	v_add_f32_e32 v4, v33, v4
	v_pk_mul_f32 v[36:37], v[36:37], v[36:37]
	v_add_f32_e32 v4, v32, v4
	v_and_b32_e32 v34, 0xffff0000, v35
	v_lshlrev_b32_e32 v35, 16, v35
	v_add_f32_e32 v4, v37, v4
	v_pk_mul_f32 v[34:35], v[34:35], v[34:35]
	v_add_f32_e32 v4, v36, v4
	v_add_f32_e32 v4, v35, v4
	v_add_f32_e32 v4, v34, v4
	v_add_f32_e32 v4, v38, v4
	s_waitcnt vmcnt(8)
	v_lshlrev_b32_e32 v22, 16, v60
	v_and_b32_e32 v23, 0xffff0000, v60
	v_pk_mul_f32 v[22:23], v[22:23], v[22:23]
	v_and_b32_e32 v60, 0xffff0000, v61
	v_lshlrev_b32_e32 v61, 16, v61
	v_pk_mul_f32 v[60:61], v[60:61], v[60:61]
	v_add_f32_e32 v5, v22, v23
	v_and_b32_e32 v24, 0xffff0000, v62
	v_lshlrev_b32_e32 v25, 16, v62
	v_add_f32_e32 v5, v61, v5
	v_pk_mul_f32 v[24:25], v[24:25], v[24:25]
	v_add_f32_e32 v5, v60, v5
	v_and_b32_e32 v62, 0xffff0000, v63
	v_lshlrev_b32_e32 v63, 16, v63
	v_add_f32_e32 v5, v25, v5
	v_pk_mul_f32 v[62:63], v[62:63], v[62:63]
	v_add_f32_e32 v5, v24, v5
	v_add_f32_e32 v5, v63, v5
	v_add_f32_e32 v5, v62, v5
	v_add_f32_e32 v62, v4, v5
	v_lshlrev_b32_e32 v4, 16, v56
	v_and_b32_e32 v5, 0xffff0000, v56
	v_pk_mul_f32 v[4:5], v[4:5], v[4:5]
	v_and_b32_e32 v56, 0xffff0000, v57
	v_lshlrev_b32_e32 v57, 16, v57
	v_pk_mul_f32 v[56:57], v[56:57], v[56:57]
	v_add_f32_e32 v4, v4, v5
	v_and_b32_e32 v60, 0xffff0000, v58
	v_lshlrev_b32_e32 v61, 16, v58
	v_add_f32_e32 v4, v57, v4
	v_pk_mul_f32 v[60:61], v[60:61], v[60:61]
	v_add_f32_e32 v4, v56, v4
	v_and_b32_e32 v58, 0xffff0000, v59
	v_lshlrev_b32_e32 v59, 16, v59
	v_add_f32_e32 v4, v61, v4
	v_pk_mul_f32 v[58:59], v[58:59], v[58:59]
	v_add_f32_e32 v4, v60, v4
	v_add_f32_e32 v4, v59, v4
	v_add_f32_e32 v4, v58, v4
	v_add_f32_e32 v58, v62, v4
	v_lshlrev_b32_e32 v4, 16, v52
	v_and_b32_e32 v5, 0xffff0000, v52
	v_pk_mul_f32 v[4:5], v[4:5], v[4:5]
	v_and_b32_e32 v52, 0xffff0000, v53
	v_lshlrev_b32_e32 v53, 16, v53
	v_pk_mul_f32 v[52:53], v[52:53], v[52:53]
	v_add_f32_e32 v4, v4, v5
	v_and_b32_e32 v56, 0xffff0000, v54
	v_lshlrev_b32_e32 v57, 16, v54
	v_add_f32_e32 v4, v53, v4
	v_pk_mul_f32 v[56:57], v[56:57], v[56:57]
	v_add_f32_e32 v4, v52, v4
	v_and_b32_e32 v54, 0xffff0000, v55
	v_lshlrev_b32_e32 v55, 16, v55
	v_add_f32_e32 v4, v57, v4
	v_pk_mul_f32 v[54:55], v[54:55], v[54:55]
	v_add_f32_e32 v4, v56, v4
	v_add_f32_e32 v4, v55, v4
	v_add_f32_e32 v4, v54, v4
	v_add_f32_e32 v54, v58, v4
	v_lshlrev_b32_e32 v4, 16, v48
	v_and_b32_e32 v5, 0xffff0000, v48
	v_pk_mul_f32 v[4:5], v[4:5], v[4:5]
	v_and_b32_e32 v48, 0xffff0000, v49
	v_lshlrev_b32_e32 v49, 16, v49
	v_pk_mul_f32 v[48:49], v[48:49], v[48:49]
	v_add_f32_e32 v4, v4, v5
	v_and_b32_e32 v52, 0xffff0000, v50
	v_lshlrev_b32_e32 v53, 16, v50
	v_add_f32_e32 v4, v49, v4
	v_pk_mul_f32 v[52:53], v[52:53], v[52:53]
	v_add_f32_e32 v4, v48, v4
	v_and_b32_e32 v50, 0xffff0000, v51
	v_lshlrev_b32_e32 v51, 16, v51
	v_add_f32_e32 v4, v53, v4
	v_pk_mul_f32 v[50:51], v[50:51], v[50:51]
	v_add_f32_e32 v4, v52, v4
	v_add_f32_e32 v4, v51, v4
	v_add_f32_e32 v4, v50, v4
	v_add_f32_e32 v4, v54, v4
	s_waitcnt vmcnt(4)
;   DI bf16_t* z() const { return (bf16_t*)(ws + OFF_Z); }
; DI float bflo(unsigned u) { return __uint_as_float(u << 16); }
; DI float bfhi(unsigned u) { return __uint_as_float(u & 0xffff0000u); }
; DI void row_rstd(const bf16_t* __restrict__ A, int lda, int K, int m0, float* rs) {
;     ...
;   for (int c = 0; c < K / 2; c += 8) {
;     const u32x4 v = *(const u32x4*)(r + c);
;     ss += bflo(v.x) * bflo(v.x) + bfhi(v.x) * bfhi(v.x) + bflo(v.y) * bflo(v.y) + bfhi(v.y) * bfhi(v.y) +
;           bflo(v.z) * bflo(v.z) + bfhi(v.z) * bfhi(v.z) + bflo(v.w) * bflo(v.w) + bfhi(v.w) * bfhi(v.w);
;   }
	v_lshlrev_b32_e32 v22, 16, v76
	v_and_b32_e32 v23, 0xffff0000, v76
	v_pk_mul_f32 v[22:23], v[22:23], v[22:23]
	v_and_b32_e32 v76, 0xffff0000, v77
	v_lshlrev_b32_e32 v77, 16, v77
	v_pk_mul_f32 v[76:77], v[76:77], v[76:77]
	v_add_f32_e32 v5, v22, v23
	v_and_b32_e32 v24, 0xffff0000, v78
	v_lshlrev_b32_e32 v25, 16, v78
	v_add_f32_e32 v5, v77, v5
	v_pk_mul_f32 v[24:25], v[24:25], v[24:25]
	v_add_f32_e32 v5, v76, v5
	v_and_b32_e32 v78, 0xffff0000, v79
	v_lshlrev_b32_e32 v79, 16, v79
	v_add_f32_e32 v5, v25, v5
	v_pk_mul_f32 v[78:79], v[78:79], v[78:79]
	v_add_f32_e32 v5, v24, v5
	v_add_f32_e32 v5, v79, v5
	v_add_f32_e32 v5, v78, v5
	v_add_f32_e32 v78, v4, v5
	v_lshlrev_b32_e32 v4, 16, v72
	v_and_b32_e32 v5, 0xffff0000, v72
	v_pk_mul_f32 v[4:5], v[4:5], v[4:5]
	v_and_b32_e32 v72, 0xffff0000, v73
	v_lshlrev_b32_e32 v73, 16, v73
	v_pk_mul_f32 v[72:73], v[72:73], v[72:73]
	v_add_f32_e32 v4, v4, v5
	v_and_b32_e32 v76, 0xffff0000, v74
	v_lshlrev_b32_e32 v77, 16, v74
	v_add_f32_e32 v4, v73, v4
	v_pk_mul_f32 v[76:77], v[76:77], v[76:77]
	v_add_f32_e32 v4, v72, v4
	v_and_b32_e32 v74, 0xffff0000, v75
	v_lshlrev_b32_e32 v75, 16, v75
	v_add_f32_e32 v4, v77, v4
	v_pk_mul_f32 v[74:75], v[74:75], v[74:75]
	v_add_f32_e32 v4, v76, v4
	v_add_f32_e32 v4, v75, v4
	v_add_f32_e32 v4, v74, v4
	v_add_f32_e32 v74, v78, v4
	v_lshlrev_b32_e32 v4, 16, v68
	v_and_b32_e32 v5, 0xffff0000, v68
	v_pk_mul_f32 v[4:5], v[4:5], v[4:5]
	v_and_b32_e32 v68, 0xffff0000, v69
	v_lshlrev_b32_e32 v69, 16, v69
	v_pk_mul_f32 v[68:69], v[68:69], v[68:69]
	v_add_f32_e32 v4, v4, v5
	v_and_b32_e32 v72, 0xffff0000, v70
	v_lshlrev_b32_e32 v73, 16, v70
	v_add_f32_e32 v4, v69, v4
	v_pk_mul_f32 v[72:73], v[72:73], v[72:73]
	v_add_f32_e32 v4, v68, v4
	v_and_b32_e32 v70, 0xffff0000, v71
	v_lshlrev_b32_e32 v71, 16, v71
	v_add_f32_e32 v4, v73, v4
	v_pk_mul_f32 v[70:71], v[70:71], v[70:71]
	v_add_f32_e32 v4, v72, v4
	v_add_f32_e32 v4, v71, v4
	v_add_f32_e32 v4, v70, v4
	v_add_f32_e32 v70, v74, v4
	v_lshlrev_b32_e32 v4, 16, v64
	v_and_b32_e32 v5, 0xffff0000, v64
	v_pk_mul_f32 v[4:5], v[4:5], v[4:5]
	v_and_b32_e32 v64, 0xffff0000, v65
	v_lshlrev_b32_e32 v65, 16, v65
	v_pk_mul_f32 v[64:65], v[64:65], v[64:65]
	v_add_f32_e32 v4, v4, v5
	v_and_b32_e32 v68, 0xffff0000, v66
	v_lshlrev_b32_e32 v69, 16, v66
	v_add_f32_e32 v4, v65, v4
	v_pk_mul_f32 v[68:69], v[68:69], v[68:69]
	v_add_f32_e32 v4, v64, v4
	v_and_b32_e32 v66, 0xffff0000, v67
	v_lshlrev_b32_e32 v67, 16, v67
	v_add_f32_e32 v4, v69, v4
	v_pk_mul_f32 v[66:67], v[66:67], v[66:67]
	v_add_f32_e32 v4, v68, v4
	v_add_f32_e32 v4, v67, v4
	v_add_f32_e32 v4, v66, v4
	v_add_f32_e32 v4, v70, v4
	s_waitcnt vmcnt(0)
	v_lshlrev_b32_e32 v22, 16, v92
	v_and_b32_e32 v23, 0xffff0000, v92
	v_pk_mul_f32 v[22:23], v[22:23], v[22:23]
	v_and_b32_e32 v92, 0xffff0000, v93
	v_lshlrev_b32_e32 v93, 16, v93
	v_pk_mul_f32 v[92:93], v[92:93], v[92:93]
	v_add_f32_e32 v5, v22, v23
	v_and_b32_e32 v24, 0xffff0000, v94
	v_lshlrev_b32_e32 v25, 16, v94
	v_add_f32_e32 v5, v93, v5
	v_pk_mul_f32 v[24:25], v[24:25], v[24:25]
	v_add_f32_e32 v5, v92, v5
	v_and_b32_e32 v94, 0xffff0000, v95
	v_lshlrev_b32_e32 v95, 16, v95
	v_add_f32_e32 v5, v25, v5
	v_pk_mul_f32 v[94:95], v[94:95], v[94:95]
	v_add_f32_e32 v5, v24, v5
	v_add_f32_e32 v5, v95, v5
	v_add_f32_e32 v5, v94, v5
	v_add_f32_e32 v94, v4, v5
	v_lshlrev_b32_e32 v4, 16, v88
	v_and_b32_e32 v5, 0xffff0000, v88
	v_pk_mul_f32 v[4:5], v[4:5], v[4:5]
	v_and_b32_e32 v88, 0xffff0000, v89
	v_lshlrev_b32_e32 v89, 16, v89
	v_pk_mul_f32 v[88:89], v[88:89], v[88:89]
	v_add_f32_e32 v4, v4, v5
	v_and_b32_e32 v92, 0xffff0000, v90
	v_lshlrev_b32_e32 v93, 16, v90
	v_add_f32_e32 v4, v89, v4
	v_pk_mul_f32 v[92:93], v[92:93], v[92:93]
	v_add_f32_e32 v4, v88, v4
	v_and_b32_e32 v90, 0xffff0000, v91
	v_lshlrev_b32_e32 v91, 16, v91
	v_add_f32_e32 v4, v93, v4
	v_pk_mul_f32 v[90:91], v[90:91], v[90:91]
	v_add_f32_e32 v4, v92, v4
	v_add_f32_e32 v4, v91, v4
	v_add_f32_e32 v4, v90, v4
	v_add_f32_e32 v90, v94, v4
	v_lshlrev_b32_e32 v4, 16, v84
	v_and_b32_e32 v5, 0xffff0000, v84
	v_pk_mul_f32 v[4:5], v[4:5], v[4:5]
	v_and_b32_e32 v84, 0xffff0000, v85
	v_lshlrev_b32_e32 v85, 16, v85
	v_pk_mul_f32 v[84:85], v[84:85], v[84:85]
	v_add_f32_e32 v4, v4, v5
	v_and_b32_e32 v88, 0xffff0000, v86
	v_lshlrev_b32_e32 v89, 16, v86
	v_add_f32_e32 v4, v85, v4
	v_pk_mul_f32 v[88:89], v[88:89], v[88:89]
	v_add_f32_e32 v4, v84, v4
	v_and_b32_e32 v86, 0xffff0000, v87
	v_lshlrev_b32_e32 v87, 16, v87
	v_add_f32_e32 v4, v89, v4
	v_pk_mul_f32 v[86:87], v[86:87], v[86:87]
	v_add_f32_e32 v4, v88, v4
	v_add_f32_e32 v4, v87, v4
	v_add_f32_e32 v4, v86, v4
	v_add_f32_e32 v86, v90, v4
	v_lshlrev_b32_e32 v4, 16, v80
	v_and_b32_e32 v5, 0xffff0000, v80
	v_pk_mul_f32 v[4:5], v[4:5], v[4:5]
	v_and_b32_e32 v80, 0xffff0000, v81
	v_lshlrev_b32_e32 v81, 16, v81
	v_pk_mul_f32 v[80:81], v[80:81], v[80:81]
	v_add_f32_e32 v4, v4, v5
	v_and_b32_e32 v84, 0xffff0000, v82
	v_lshlrev_b32_e32 v85, 16, v82
	v_add_f32_e32 v4, v81, v4
	v_pk_mul_f32 v[84:85], v[84:85], v[84:85]
	v_add_f32_e32 v4, v80, v4
	v_and_b32_e32 v82, 0xffff0000, v83
	v_lshlrev_b32_e32 v83, 16, v83
	v_add_f32_e32 v4, v85, v4
	v_pk_mul_f32 v[82:83], v[82:83], v[82:83]
	v_add_f32_e32 v4, v84, v4
	v_add_f32_e32 v4, v83, v4
	v_add_f32_e32 v4, v82, v4
	v_add_f32_e32 v4, v86, v4
	global_load_dwordx4 v[44:47], v[0:1], off offset:224
	global_load_dwordx4 v[40:43], v[0:1], off offset:240
	global_load_dwordx4 v[36:39], v[0:1], off offset:256
	global_load_dwordx4 v[32:35], v[0:1], off offset:272
	global_load_dwordx4 v[60:63], v[0:1], off offset:288
	global_load_dwordx4 v[56:59], v[0:1], off offset:304
	global_load_dwordx4 v[52:55], v[0:1], off offset:320
	global_load_dwordx4 v[48:51], v[0:1], off offset:336
	global_load_dwordx4 v[76:79], v[0:1], off offset:352
	global_load_dwordx4 v[72:75], v[0:1], off offset:368
	global_load_dwordx4 v[68:71], v[0:1], off offset:384
	global_load_dwordx4 v[64:67], v[0:1], off offset:400
	global_load_dwordx4 v[92:95], v[0:1], off offset:416
	global_load_dwordx4 v[88:91], v[0:1], off offset:432
	global_load_dwordx4 v[84:87], v[0:1], off offset:448
	global_load_dwordx4 v[80:83], v[0:1], off offset:464
	s_waitcnt vmcnt(12)
;   DI bf16_t* z() const { return (bf16_t*)(ws + OFF_Z); }
; DI float bflo(unsigned u) { return __uint_as_float(u << 16); }
; DI float bfhi(unsigned u) { return __uint_as_float(u & 0xffff0000u); }
; DI void row_rstd(const bf16_t* __restrict__ A, int lda, int K, int m0, float* rs) {
;     ...
;   for (int c = 0; c < K / 2; c += 8) {
;     const u32x4 v = *(const u32x4*)(r + c);
;     ss += bflo(v.x) * bflo(v.x) + bfhi(v.x) * bfhi(v.x) + bflo(v.y) * bflo(v.y) + bfhi(v.y) * bfhi(v.y) +
;           bflo(v.z) * bflo(v.z) + bfhi(v.z) * bfhi(v.z) + bflo(v.w) * bflo(v.w) + bfhi(v.w) * bfhi(v.w);
;   }
	v_lshlrev_b32_e32 v22, 16, v44
	v_and_b32_e32 v23, 0xffff0000, v44
	v_pk_mul_f32 v[22:23], v[22:23], v[22:23]
	v_and_b32_e32 v44, 0xffff0000, v45
	v_lshlrev_b32_e32 v45, 16, v45
	v_pk_mul_f32 v[44:45], v[44:45], v[44:45]
	v_add_f32_e32 v5, v22, v23
	v_and_b32_e32 v24, 0xffff0000, v46
	v_lshlrev_b32_e32 v25, 16, v46
	v_add_f32_e32 v5, v45, v5
	v_pk_mul_f32 v[24:25], v[24:25], v[24:25]
	v_add_f32_e32 v5, v44, v5
	v_and_b32_e32 v46, 0xffff0000, v47
	v_lshlrev_b32_e32 v47, 16, v47
	v_add_f32_e32 v5, v25, v5
	v_pk_mul_f32 v[46:47], v[46:47], v[46:47]
	v_add_f32_e32 v5, v24, v5
	v_add_f32_e32 v5, v47, v5
	v_add_f32_e32 v5, v46, v5
	v_add_f32_e32 v46, v4, v5
	v_lshlrev_b32_e32 v4, 16, v40
	v_and_b32_e32 v5, 0xffff0000, v40
	v_pk_mul_f32 v[4:5], v[4:5], v[4:5]
	v_and_b32_e32 v40, 0xffff0000, v41
	v_lshlrev_b32_e32 v41, 16, v41
	v_pk_mul_f32 v[40:41], v[40:41], v[40:41]
	v_add_f32_e32 v4, v4, v5
	v_and_b32_e32 v44, 0xffff0000, v42
	v_lshlrev_b32_e32 v45, 16, v42
	v_add_f32_e32 v4, v41, v4
	v_pk_mul_f32 v[44:45], v[44:45], v[44:45]
	v_add_f32_e32 v4, v40, v4
	v_and_b32_e32 v42, 0xffff0000, v43
	v_lshlrev_b32_e32 v43, 16, v43
	v_add_f32_e32 v4, v45, v4
	v_pk_mul_f32 v[42:43], v[42:43], v[42:43]
	v_add_f32_e32 v4, v44, v4
	v_add_f32_e32 v4, v43, v4
	v_add_f32_e32 v4, v42, v4
	v_add_f32_e32 v42, v46, v4
	v_lshlrev_b32_e32 v4, 16, v36
	v_and_b32_e32 v5, 0xffff0000, v36
	v_pk_mul_f32 v[4:5], v[4:5], v[4:5]
	v_and_b32_e32 v36, 0xffff0000, v37
	v_lshlrev_b32_e32 v37, 16, v37
	v_pk_mul_f32 v[36:37], v[36:37], v[36:37]
	v_add_f32_e32 v4, v4, v5
	v_and_b32_e32 v40, 0xffff0000, v38
	v_lshlrev_b32_e32 v41, 16, v38
	v_add_f32_e32 v4, v37, v4
	v_pk_mul_f32 v[40:41], v[40:41], v[40:41]
	v_add_f32_e32 v4, v36, v4
	v_and_b32_e32 v38, 0xffff0000, v39
	v_lshlrev_b32_e32 v39, 16, v39
	v_add_f32_e32 v4, v41, v4
	v_pk_mul_f32 v[38:39], v[38:39], v[38:39]
	v_add_f32_e32 v4, v40, v4
	v_add_f32_e32 v4, v39, v4
	v_add_f32_e32 v4, v38, v4
	v_add_f32_e32 v38, v42, v4
	v_lshlrev_b32_e32 v4, 16, v32
	v_and_b32_e32 v5, 0xffff0000, v32
	v_pk_mul_f32 v[4:5], v[4:5], v[4:5]
	v_and_b32_e32 v32, 0xffff0000, v33
	v_lshlrev_b32_e32 v33, 16, v33
	v_pk_mul_f32 v[32:33], v[32:33], v[32:33]
	v_add_f32_e32 v4, v4, v5
	v_and_b32_e32 v36, 0xffff0000, v34
	v_lshlrev_b32_e32 v37, 16, v34
	v_add_f32_e32 v4, v33, v4
	v_pk_mul_f32 v[36:37], v[36:37], v[36:37]
	v_add_f32_e32 v4, v32, v4
	v_and_b32_e32 v34, 0xffff0000, v35
	v_lshlrev_b32_e32 v35, 16, v35
	v_add_f32_e32 v4, v37, v4
	v_pk_mul_f32 v[34:35], v[34:35], v[34:35]
	v_add_f32_e32 v4, v36, v4
	v_add_f32_e32 v4, v35, v4
	v_add_f32_e32 v4, v34, v4
	v_add_f32_e32 v4, v38, v4
	s_waitcnt vmcnt(8)
	v_lshlrev_b32_e32 v22, 16, v60
	v_and_b32_e32 v23, 0xffff0000, v60
	v_pk_mul_f32 v[22:23], v[22:23], v[22:23]
	v_and_b32_e32 v60, 0xffff0000, v61
	v_lshlrev_b32_e32 v61, 16, v61
	v_pk_mul_f32 v[60:61], v[60:61], v[60:61]
	v_add_f32_e32 v5, v22, v23
	v_and_b32_e32 v24, 0xffff0000, v62
	v_lshlrev_b32_e32 v25, 16, v62
	v_add_f32_e32 v5, v61, v5
	v_pk_mul_f32 v[24:25], v[24:25], v[24:25]
	v_add_f32_e32 v5, v60, v5
	v_and_b32_e32 v62, 0xffff0000, v63
	v_lshlrev_b32_e32 v63, 16, v63
	v_add_f32_e32 v5, v25, v5
	v_pk_mul_f32 v[62:63], v[62:63], v[62:63]
	v_add_f32_e32 v5, v24, v5
	v_add_f32_e32 v5, v63, v5
	v_add_f32_e32 v5, v62, v5
	v_add_f32_e32 v62, v4, v5
	v_lshlrev_b32_e32 v4, 16, v56
	v_and_b32_e32 v5, 0xffff0000, v56
	v_pk_mul_f32 v[4:5], v[4:5], v[4:5]
	v_and_b32_e32 v56, 0xffff0000, v57
	v_lshlrev_b32_e32 v57, 16, v57
	v_pk_mul_f32 v[56:57], v[56:57], v[56:57]
	v_add_f32_e32 v4, v4, v5
	v_and_b32_e32 v60, 0xffff0000, v58
	v_lshlrev_b32_e32 v61, 16, v58
	v_add_f32_e32 v4, v57, v4
	v_pk_mul_f32 v[60:61], v[60:61], v[60:61]
	v_add_f32_e32 v4, v56, v4
	v_and_b32_e32 v58, 0xffff0000, v59
	v_lshlrev_b32_e32 v59, 16, v59
	v_add_f32_e32 v4, v61, v4
	v_pk_mul_f32 v[58:59], v[58:59], v[58:59]
	v_add_f32_e32 v4, v60, v4
	v_add_f32_e32 v4, v59, v4
	v_add_f32_e32 v4, v58, v4
	v_add_f32_e32 v58, v62, v4
	v_lshlrev_b32_e32 v4, 16, v52
	v_and_b32_e32 v5, 0xffff0000, v52
	v_pk_mul_f32 v[4:5], v[4:5], v[4:5]
	v_and_b32_e32 v52, 0xffff0000, v53
	v_lshlrev_b32_e32 v53, 16, v53
	v_pk_mul_f32 v[52:53], v[52:53], v[52:53]
	v_add_f32_e32 v4, v4, v5
	v_and_b32_e32 v56, 0xffff0000, v54
	v_lshlrev_b32_e32 v57, 16, v54
	v_add_f32_e32 v4, v53, v4
	v_pk_mul_f32 v[56:57], v[56:57], v[56:57]
	v_add_f32_e32 v4, v52, v4
	v_and_b32_e32 v54, 0xffff0000, v55
	v_lshlrev_b32_e32 v55, 16, v55
	v_add_f32_e32 v4, v57, v4
	v_pk_mul_f32 v[54:55], v[54:55], v[54:55]
	v_add_f32_e32 v4, v56, v4
	v_add_f32_e32 v4, v55, v4
	v_add_f32_e32 v4, v54, v4
	v_add_f32_e32 v54, v58, v4
	v_lshlrev_b32_e32 v4, 16, v48
	v_and_b32_e32 v5, 0xffff0000, v48
	v_pk_mul_f32 v[4:5], v[4:5], v[4:5]
	v_and_b32_e32 v48, 0xffff0000, v49
	v_lshlrev_b32_e32 v49, 16, v49
	v_pk_mul_f32 v[48:49], v[48:49], v[48:49]
	v_add_f32_e32 v4, v4, v5
	v_and_b32_e32 v52, 0xffff0000, v50
	v_lshlrev_b32_e32 v53, 16, v50
	v_add_f32_e32 v4, v49, v4
	v_pk_mul_f32 v[52:53], v[52:53], v[52:53]
	v_add_f32_e32 v4, v48, v4
	v_and_b32_e32 v50, 0xffff0000, v51
	v_lshlrev_b32_e32 v51, 16, v51
	v_add_f32_e32 v4, v53, v4
	v_pk_mul_f32 v[50:51], v[50:51], v[50:51]
	v_add_f32_e32 v4, v52, v4
	v_add_f32_e32 v4, v51, v4
	v_add_f32_e32 v4, v50, v4
	v_add_f32_e32 v4, v54, v4
	s_waitcnt vmcnt(4)
;   DI bf16_t* z() const { return (bf16_t*)(ws + OFF_Z); }
; DI float bflo(unsigned u) { return __uint_as_float(u << 16); }
; DI float bfhi(unsigned u) { return __uint_as_float(u & 0xffff0000u); }
; DI void row_rstd(const bf16_t* __restrict__ A, int lda, int K, int m0, float* rs) {
;     ...
;   for (int c = 0; c < K / 2; c += 8) {
;     const u32x4 v = *(const u32x4*)(r + c);
;     ss += bflo(v.x) * bflo(v.x) + bfhi(v.x) * bfhi(v.x) + bflo(v.y) * bflo(v.y) + bfhi(v.y) * bfhi(v.y) +
;           bflo(v.z) * bflo(v.z) + bfhi(v.z) * bfhi(v.z) + bflo(v.w) * bflo(v.w) + bfhi(v.w) * bfhi(v.w);
;   }
	v_lshlrev_b32_e32 v22, 16, v76
	v_and_b32_e32 v23, 0xffff0000, v76
	v_pk_mul_f32 v[22:23], v[22:23], v[22:23]
	v_and_b32_e32 v76, 0xffff0000, v77
	v_lshlrev_b32_e32 v77, 16, v77
	v_pk_mul_f32 v[76:77], v[76:77], v[76:77]
	v_add_f32_e32 v5, v22, v23
	v_and_b32_e32 v24, 0xffff0000, v78
	v_lshlrev_b32_e32 v25, 16, v78
	v_add_f32_e32 v5, v77, v5
	v_pk_mul_f32 v[24:25], v[24:25], v[24:25]
	v_add_f32_e32 v5, v76, v5
	v_and_b32_e32 v78, 0xffff0000, v79
	v_lshlrev_b32_e32 v79, 16, v79
	v_add_f32_e32 v5, v25, v5
	v_pk_mul_f32 v[78:79], v[78:79], v[78:79]
	v_add_f32_e32 v5, v24, v5
	v_add_f32_e32 v5, v79, v5
	v_add_f32_e32 v5, v78, v5
	v_add_f32_e32 v78, v4, v5
	v_lshlrev_b32_e32 v4, 16, v72
	v_and_b32_e32 v5, 0xffff0000, v72
	v_pk_mul_f32 v[4:5], v[4:5], v[4:5]
	v_and_b32_e32 v72, 0xffff0000, v73
	v_lshlrev_b32_e32 v73, 16, v73
	v_pk_mul_f32 v[72:73], v[72:73], v[72:73]
	v_add_f32_e32 v4, v4, v5
	v_and_b32_e32 v76, 0xffff0000, v74
	v_lshlrev_b32_e32 v77, 16, v74
	v_add_f32_e32 v4, v73, v4
	v_pk_mul_f32 v[76:77], v[76:77], v[76:77]
	v_add_f32_e32 v4, v72, v4
	v_and_b32_e32 v74, 0xffff0000, v75
	v_lshlrev_b32_e32 v75, 16, v75
	v_add_f32_e32 v4, v77, v4
	v_pk_mul_f32 v[74:75], v[74:75], v[74:75]
	v_add_f32_e32 v4, v76, v4
	v_add_f32_e32 v4, v75, v4
	v_add_f32_e32 v4, v74, v4
	v_add_f32_e32 v74, v78, v4
	v_lshlrev_b32_e32 v4, 16, v68
	v_and_b32_e32 v5, 0xffff0000, v68
	v_pk_mul_f32 v[4:5], v[4:5], v[4:5]
	v_and_b32_e32 v68, 0xffff0000, v69
	v_lshlrev_b32_e32 v69, 16, v69
	v_pk_mul_f32 v[68:69], v[68:69], v[68:69]
	v_add_f32_e32 v4, v4, v5
	v_and_b32_e32 v72, 0xffff0000, v70
	v_lshlrev_b32_e32 v73, 16, v70
	v_add_f32_e32 v4, v69, v4
	v_pk_mul_f32 v[72:73], v[72:73], v[72:73]
	v_add_f32_e32 v4, v68, v4
	v_and_b32_e32 v70, 0xffff0000, v71
	v_lshlrev_b32_e32 v71, 16, v71
	v_add_f32_e32 v4, v73, v4
	v_pk_mul_f32 v[70:71], v[70:71], v[70:71]
	v_add_f32_e32 v4, v72, v4
	v_add_f32_e32 v4, v71, v4
	v_add_f32_e32 v4, v70, v4
	v_add_f32_e32 v70, v74, v4
	v_lshlrev_b32_e32 v4, 16, v64
	v_and_b32_e32 v5, 0xffff0000, v64
	v_pk_mul_f32 v[4:5], v[4:5], v[4:5]
	v_and_b32_e32 v64, 0xffff0000, v65
	v_lshlrev_b32_e32 v65, 16, v65
	v_pk_mul_f32 v[64:65], v[64:65], v[64:65]
	v_add_f32_e32 v4, v4, v5
	v_and_b32_e32 v68, 0xffff0000, v66
	v_lshlrev_b32_e32 v69, 16, v66
	v_add_f32_e32 v4, v65, v4
	v_pk_mul_f32 v[68:69], v[68:69], v[68:69]
	v_add_f32_e32 v4, v64, v4
	v_and_b32_e32 v66, 0xffff0000, v67
	v_lshlrev_b32_e32 v67, 16, v67
	v_add_f32_e32 v4, v69, v4
	v_pk_mul_f32 v[66:67], v[66:67], v[66:67]
	v_add_f32_e32 v4, v68, v4
	v_add_f32_e32 v4, v67, v4
	v_add_f32_e32 v4, v66, v4
	v_add_f32_e32 v4, v70, v4
	s_waitcnt vmcnt(0)
	v_lshlrev_b32_e32 v22, 16, v92
	v_and_b32_e32 v23, 0xffff0000, v92
	v_pk_mul_f32 v[22:23], v[22:23], v[22:23]
	v_and_b32_e32 v92, 0xffff0000, v93
	v_lshlrev_b32_e32 v93, 16, v93
	v_pk_mul_f32 v[92:93], v[92:93], v[92:93]
	v_add_f32_e32 v5, v22, v23
	v_and_b32_e32 v24, 0xffff0000, v94
	v_lshlrev_b32_e32 v25, 16, v94
	v_add_f32_e32 v5, v93, v5
	v_pk_mul_f32 v[24:25], v[24:25], v[24:25]
	v_add_f32_e32 v5, v92, v5
	v_and_b32_e32 v94, 0xffff0000, v95
	v_lshlrev_b32_e32 v95, 16, v95
	v_add_f32_e32 v5, v25, v5
	v_pk_mul_f32 v[94:95], v[94:95], v[94:95]
	v_add_f32_e32 v5, v24, v5
	v_add_f32_e32 v5, v95, v5
	v_add_f32_e32 v5, v94, v5
	v_add_f32_e32 v94, v4, v5
	v_lshlrev_b32_e32 v4, 16, v88
	v_and_b32_e32 v5, 0xffff0000, v88
	v_pk_mul_f32 v[4:5], v[4:5], v[4:5]
	v_and_b32_e32 v88, 0xffff0000, v89
	v_lshlrev_b32_e32 v89, 16, v89
	v_pk_mul_f32 v[88:89], v[88:89], v[88:89]
	v_add_f32_e32 v4, v4, v5
	v_and_b32_e32 v92, 0xffff0000, v90
	v_lshlrev_b32_e32 v93, 16, v90
	v_add_f32_e32 v4, v89, v4
	v_pk_mul_f32 v[92:93], v[92:93], v[92:93]
	v_add_f32_e32 v4, v88, v4
	v_and_b32_e32 v90, 0xffff0000, v91
	v_lshlrev_b32_e32 v91, 16, v91
	v_add_f32_e32 v4, v93, v4
	v_pk_mul_f32 v[90:91], v[90:91], v[90:91]
	v_add_f32_e32 v4, v92, v4
	v_add_f32_e32 v4, v91, v4
	v_add_f32_e32 v4, v90, v4
	v_add_f32_e32 v90, v94, v4
	v_lshlrev_b32_e32 v4, 16, v84
	v_and_b32_e32 v5, 0xffff0000, v84
	v_pk_mul_f32 v[4:5], v[4:5], v[4:5]
	v_and_b32_e32 v84, 0xffff0000, v85
	v_lshlrev_b32_e32 v85, 16, v85
	v_pk_mul_f32 v[84:85], v[84:85], v[84:85]
	v_add_f32_e32 v4, v4, v5
	v_and_b32_e32 v88, 0xffff0000, v86
	v_lshlrev_b32_e32 v89, 16, v86
	v_add_f32_e32 v4, v85, v4
	v_pk_mul_f32 v[88:89], v[88:89], v[88:89]
	v_add_f32_e32 v4, v84, v4
	v_and_b32_e32 v86, 0xffff0000, v87
	v_lshlrev_b32_e32 v87, 16, v87
	v_add_f32_e32 v4, v89, v4
	v_pk_mul_f32 v[86:87], v[86:87], v[86:87]
	v_add_f32_e32 v4, v88, v4
	v_add_f32_e32 v4, v87, v4
	v_add_f32_e32 v4, v86, v4
	v_add_f32_e32 v86, v90, v4
	v_lshlrev_b32_e32 v4, 16, v80
	v_and_b32_e32 v5, 0xffff0000, v80
	v_pk_mul_f32 v[4:5], v[4:5], v[4:5]
	v_and_b32_e32 v80, 0xffff0000, v81
	v_lshlrev_b32_e32 v81, 16, v81
	v_pk_mul_f32 v[80:81], v[80:81], v[80:81]
	v_add_f32_e32 v4, v4, v5
	v_and_b32_e32 v84, 0xffff0000, v82
	v_lshlrev_b32_e32 v85, 16, v82
	v_add_f32_e32 v4, v81, v4
	v_pk_mul_f32 v[84:85], v[84:85], v[84:85]
	v_add_f32_e32 v4, v80, v4
	v_and_b32_e32 v82, 0xffff0000, v83
	v_lshlrev_b32_e32 v83, 16, v83
	v_add_f32_e32 v4, v85, v4
	v_pk_mul_f32 v[82:83], v[82:83], v[82:83]
	v_add_f32_e32 v4, v84, v4
	v_add_f32_e32 v4, v83, v4
	v_add_f32_e32 v4, v82, v4
	v_add_f32_e32 v4, v86, v4
	global_load_dwordx4 v[44:47], v[0:1], off offset:480
	global_load_dwordx4 v[40:43], v[0:1], off offset:496
	global_load_dwordx4 v[36:39], v[0:1], off offset:512
	global_load_dwordx4 v[32:35], v[0:1], off offset:528
	global_load_dwordx4 v[60:63], v[0:1], off offset:544
	global_load_dwordx4 v[56:59], v[0:1], off offset:560
	global_load_dwordx4 v[52:55], v[0:1], off offset:576
	global_load_dwordx4 v[48:51], v[0:1], off offset:592
	global_load_dwordx4 v[76:79], v[0:1], off offset:608
	global_load_dwordx4 v[72:75], v[0:1], off offset:624
	global_load_dwordx4 v[68:71], v[0:1], off offset:640
	global_load_dwordx4 v[64:67], v[0:1], off offset:656
	global_load_dwordx4 v[92:95], v[0:1], off offset:672
	global_load_dwordx4 v[88:91], v[0:1], off offset:688
	global_load_dwordx4 v[84:87], v[0:1], off offset:704
	global_load_dwordx4 v[80:83], v[0:1], off offset:720
	s_waitcnt vmcnt(12)
;   DI bf16_t* z() const { return (bf16_t*)(ws + OFF_Z); }
; DI float bflo(unsigned u) { return __uint_as_float(u << 16); }
; DI float bfhi(unsigned u) { return __uint_as_float(u & 0xffff0000u); }
; DI void row_rstd(const bf16_t* __restrict__ A, int lda, int K, int m0, float* rs) {
;     ...
;   for (int c = 0; c < K / 2; c += 8) {
;     const u32x4 v = *(const u32x4*)(r + c);
;     ss += bflo(v.x) * bflo(v.x) + bfhi(v.x) * bfhi(v.x) + bflo(v.y) * bflo(v.y) + bfhi(v.y) * bfhi(v.y) +
;           bflo(v.z) * bflo(v.z) + bfhi(v.z) * bfhi(v.z) + bflo(v.w) * bflo(v.w) + bfhi(v.w) * bfhi(v.w);
;   }
	v_lshlrev_b32_e32 v22, 16, v44
	v_and_b32_e32 v23, 0xffff0000, v44
	v_pk_mul_f32 v[22:23], v[22:23], v[22:23]
	v_and_b32_e32 v44, 0xffff0000, v45
	v_lshlrev_b32_e32 v45, 16, v45
	v_pk_mul_f32 v[44:45], v[44:45], v[44:45]
	v_add_f32_e32 v5, v22, v23
	v_and_b32_e32 v24, 0xffff0000, v46
	v_lshlrev_b32_e32 v25, 16, v46
	v_add_f32_e32 v5, v45, v5
	v_pk_mul_f32 v[24:25], v[24:25], v[24:25]
	v_add_f32_e32 v5, v44, v5
	v_and_b32_e32 v46, 0xffff0000, v47
	v_lshlrev_b32_e32 v47, 16, v47
	v_add_f32_e32 v5, v25, v5
	v_pk_mul_f32 v[46:47], v[46:47], v[46:47]
	v_add_f32_e32 v5, v24, v5
	v_add_f32_e32 v5, v47, v5
	v_add_f32_e32 v5, v46, v5
	v_add_f32_e32 v46, v4, v5
	v_lshlrev_b32_e32 v4, 16, v40
	v_and_b32_e32 v5, 0xffff0000, v40
	v_pk_mul_f32 v[4:5], v[4:5], v[4:5]
	v_and_b32_e32 v40, 0xffff0000, v41
	v_lshlrev_b32_e32 v41, 16, v41
	v_pk_mul_f32 v[40:41], v[40:41], v[40:41]
	v_add_f32_e32 v4, v4, v5
	v_and_b32_e32 v44, 0xffff0000, v42
	v_lshlrev_b32_e32 v45, 16, v42
	v_add_f32_e32 v4, v41, v4
	v_pk_mul_f32 v[44:45], v[44:45], v[44:45]
	v_add_f32_e32 v4, v40, v4
	v_and_b32_e32 v42, 0xffff0000, v43
	v_lshlrev_b32_e32 v43, 16, v43
	v_add_f32_e32 v4, v45, v4
	v_pk_mul_f32 v[42:43], v[42:43], v[42:43]
	v_add_f32_e32 v4, v44, v4
	v_add_f32_e32 v4, v43, v4
	v_add_f32_e32 v4, v42, v4
	v_add_f32_e32 v42, v46, v4
	v_lshlrev_b32_e32 v4, 16, v36
	v_and_b32_e32 v5, 0xffff0000, v36
	v_pk_mul_f32 v[4:5], v[4:5], v[4:5]
	v_and_b32_e32 v36, 0xffff0000, v37
	v_lshlrev_b32_e32 v37, 16, v37
	v_pk_mul_f32 v[36:37], v[36:37], v[36:37]
	v_add_f32_e32 v4, v4, v5
	v_and_b32_e32 v40, 0xffff0000, v38
	v_lshlrev_b32_e32 v41, 16, v38
	v_add_f32_e32 v4, v37, v4
	v_pk_mul_f32 v[40:41], v[40:41], v[40:41]
	v_add_f32_e32 v4, v36, v4
	v_and_b32_e32 v38, 0xffff0000, v39
	v_lshlrev_b32_e32 v39, 16, v39
	v_add_f32_e32 v4, v41, v4
	v_pk_mul_f32 v[38:39], v[38:39], v[38:39]
	v_add_f32_e32 v4, v40, v4
	v_add_f32_e32 v4, v39, v4
	v_add_f32_e32 v4, v38, v4
	v_add_f32_e32 v38, v42, v4
	v_lshlrev_b32_e32 v4, 16, v32
	v_and_b32_e32 v5, 0xffff0000, v32
	v_pk_mul_f32 v[4:5], v[4:5], v[4:5]
	v_and_b32_e32 v32, 0xffff0000, v33
	v_lshlrev_b32_e32 v33, 16, v33
	v_pk_mul_f32 v[32:33], v[32:33], v[32:33]
	v_add_f32_e32 v4, v4, v5
	v_and_b32_e32 v36, 0xffff0000, v34
	v_lshlrev_b32_e32 v37, 16, v34
	v_add_f32_e32 v4, v33, v4
	v_pk_mul_f32 v[36:37], v[36:37], v[36:37]
	v_add_f32_e32 v4, v32, v4
	v_and_b32_e32 v34, 0xffff0000, v35
	v_lshlrev_b32_e32 v35, 16, v35
	v_add_f32_e32 v4, v37, v4
	v_pk_mul_f32 v[34:35], v[34:35], v[34:35]
	v_add_f32_e32 v4, v36, v4
	v_add_f32_e32 v4, v35, v4
	v_add_f32_e32 v4, v34, v4
	v_add_f32_e32 v4, v38, v4
	s_waitcnt vmcnt(8)
	v_lshlrev_b32_e32 v22, 16, v60
	v_and_b32_e32 v23, 0xffff0000, v60
	v_pk_mul_f32 v[22:23], v[22:23], v[22:23]
	v_and_b32_e32 v60, 0xffff0000, v61
	v_lshlrev_b32_e32 v61, 16, v61
	v_pk_mul_f32 v[60:61], v[60:61], v[60:61]
	v_add_f32_e32 v5, v22, v23
	v_and_b32_e32 v24, 0xffff0000, v62
	v_lshlrev_b32_e32 v25, 16, v62
	v_add_f32_e32 v5, v61, v5
	v_pk_mul_f32 v[24:25], v[24:25], v[24:25]
	v_add_f32_e32 v5, v60, v5
	v_and_b32_e32 v62, 0xffff0000, v63
	v_lshlrev_b32_e32 v63, 16, v63
	v_add_f32_e32 v5, v25, v5
	v_pk_mul_f32 v[62:63], v[62:63], v[62:63]
	v_add_f32_e32 v5, v24, v5
	v_add_f32_e32 v5, v63, v5
	v_add_f32_e32 v5, v62, v5
	v_add_f32_e32 v62, v4, v5
	v_lshlrev_b32_e32 v4, 16, v56
	v_and_b32_e32 v5, 0xffff0000, v56
	v_pk_mul_f32 v[4:5], v[4:5], v[4:5]
	v_and_b32_e32 v56, 0xffff0000, v57
	v_lshlrev_b32_e32 v57, 16, v57
	v_pk_mul_f32 v[56:57], v[56:57], v[56:57]
	v_add_f32_e32 v4, v4, v5
	v_and_b32_e32 v60, 0xffff0000, v58
	v_lshlrev_b32_e32 v61, 16, v58
	v_add_f32_e32 v4, v57, v4
	v_pk_mul_f32 v[60:61], v[60:61], v[60:61]
	v_add_f32_e32 v4, v56, v4
	v_and_b32_e32 v58, 0xffff0000, v59
	v_lshlrev_b32_e32 v59, 16, v59
	v_add_f32_e32 v4, v61, v4
	v_pk_mul_f32 v[58:59], v[58:59], v[58:59]
	v_add_f32_e32 v4, v60, v4
	v_add_f32_e32 v4, v59, v4
	v_add_f32_e32 v4, v58, v4
	v_add_f32_e32 v58, v62, v4
	v_lshlrev_b32_e32 v4, 16, v52
	v_and_b32_e32 v5, 0xffff0000, v52
	v_pk_mul_f32 v[4:5], v[4:5], v[4:5]
	v_and_b32_e32 v52, 0xffff0000, v53
	v_lshlrev_b32_e32 v53, 16, v53
	v_pk_mul_f32 v[52:53], v[52:53], v[52:53]
	v_add_f32_e32 v4, v4, v5
	v_and_b32_e32 v56, 0xffff0000, v54
	v_lshlrev_b32_e32 v57, 16, v54
	v_add_f32_e32 v4, v53, v4
	v_pk_mul_f32 v[56:57], v[56:57], v[56:57]
	v_add_f32_e32 v4, v52, v4
	v_and_b32_e32 v54, 0xffff0000, v55
	v_lshlrev_b32_e32 v55, 16, v55
	v_add_f32_e32 v4, v57, v4
	v_pk_mul_f32 v[54:55], v[54:55], v[54:55]
	v_add_f32_e32 v4, v56, v4
	v_add_f32_e32 v4, v55, v4
	v_add_f32_e32 v4, v54, v4
	v_add_f32_e32 v54, v58, v4
	v_lshlrev_b32_e32 v4, 16, v48
	v_and_b32_e32 v5, 0xffff0000, v48
	v_pk_mul_f32 v[4:5], v[4:5], v[4:5]
	v_and_b32_e32 v48, 0xffff0000, v49
	v_lshlrev_b32_e32 v49, 16, v49
	v_pk_mul_f32 v[48:49], v[48:49], v[48:49]
	v_add_f32_e32 v4, v4, v5
	v_and_b32_e32 v52, 0xffff0000, v50
	v_lshlrev_b32_e32 v53, 16, v50
	v_add_f32_e32 v4, v49, v4
	v_pk_mul_f32 v[52:53], v[52:53], v[52:53]
	v_add_f32_e32 v4, v48, v4
	v_and_b32_e32 v50, 0xffff0000, v51
	v_lshlrev_b32_e32 v51, 16, v51
	v_add_f32_e32 v4, v53, v4
	v_pk_mul_f32 v[50:51], v[50:51], v[50:51]
	v_add_f32_e32 v4, v52, v4
	v_add_f32_e32 v4, v51, v4
	v_add_f32_e32 v4, v50, v4
	v_add_f32_e32 v4, v54, v4
	s_waitcnt vmcnt(4)
;   DI bf16_t* z() const { return (bf16_t*)(ws + OFF_Z); }
; DI float bflo(unsigned u) { return __uint_as_float(u << 16); }
; DI float bfhi(unsigned u) { return __uint_as_float(u & 0xffff0000u); }
; DI void row_rstd(const bf16_t* __restrict__ A, int lda, int K, int m0, float* rs) {
;     ...
;   for (int c = 0; c < K / 2; c += 8) {
;     const u32x4 v = *(const u32x4*)(r + c);
;     ss += bflo(v.x) * bflo(v.x) + bfhi(v.x) * bfhi(v.x) + bflo(v.y) * bflo(v.y) + bfhi(v.y) * bfhi(v.y) +
;           bflo(v.z) * bflo(v.z) + bfhi(v.z) * bfhi(v.z) + bflo(v.w) * bflo(v.w) + bfhi(v.w) * bfhi(v.w);
;   }
;   ss += __shfl_xor(ss, 1);
;   if ((tid & 1) == 0) rs[tid >> 1] = rsqrtf(ss / (float)K + EPS);
;   __syncthreads();
	v_lshlrev_b32_e32 v22, 16, v76
	v_and_b32_e32 v23, 0xffff0000, v76
	v_pk_mul_f32 v[22:23], v[22:23], v[22:23]
	v_and_b32_e32 v76, 0xffff0000, v77
	v_lshlrev_b32_e32 v77, 16, v77
	v_pk_mul_f32 v[76:77], v[76:77], v[76:77]
	v_add_f32_e32 v5, v22, v23
	v_and_b32_e32 v24, 0xffff0000, v78
	v_lshlrev_b32_e32 v25, 16, v78
	v_add_f32_e32 v5, v77, v5
	v_pk_mul_f32 v[24:25], v[24:25], v[24:25]
	v_add_f32_e32 v5, v76, v5
	v_and_b32_e32 v78, 0xffff0000, v79
	v_lshlrev_b32_e32 v79, 16, v79
	v_add_f32_e32 v5, v25, v5
	v_pk_mul_f32 v[78:79], v[78:79], v[78:79]
	v_add_f32_e32 v5, v24, v5
	v_add_f32_e32 v5, v79, v5
	v_add_f32_e32 v5, v78, v5
	v_add_f32_e32 v78, v4, v5
	v_lshlrev_b32_e32 v4, 16, v72
	v_and_b32_e32 v5, 0xffff0000, v72
	v_pk_mul_f32 v[4:5], v[4:5], v[4:5]
	v_and_b32_e32 v72, 0xffff0000, v73
	v_lshlrev_b32_e32 v73, 16, v73
	v_pk_mul_f32 v[72:73], v[72:73], v[72:73]
	v_add_f32_e32 v4, v4, v5
	v_and_b32_e32 v76, 0xffff0000, v74
	v_lshlrev_b32_e32 v77, 16, v74
	v_add_f32_e32 v4, v73, v4
	v_pk_mul_f32 v[76:77], v[76:77], v[76:77]
	v_add_f32_e32 v4, v72, v4
	v_and_b32_e32 v74, 0xffff0000, v75
	v_lshlrev_b32_e32 v75, 16, v75
	v_add_f32_e32 v4, v77, v4
	v_pk_mul_f32 v[74:75], v[74:75], v[74:75]
	v_add_f32_e32 v4, v76, v4
	v_add_f32_e32 v4, v75, v4
	v_add_f32_e32 v4, v74, v4
	v_add_f32_e32 v74, v78, v4
	v_lshlrev_b32_e32 v4, 16, v68
	v_and_b32_e32 v5, 0xffff0000, v68
	v_pk_mul_f32 v[4:5], v[4:5], v[4:5]
	v_and_b32_e32 v68, 0xffff0000, v69
	v_lshlrev_b32_e32 v69, 16, v69
	v_pk_mul_f32 v[68:69], v[68:69], v[68:69]
	v_add_f32_e32 v4, v4, v5
	v_and_b32_e32 v72, 0xffff0000, v70
	v_lshlrev_b32_e32 v73, 16, v70
	v_add_f32_e32 v4, v69, v4
	v_pk_mul_f32 v[72:73], v[72:73], v[72:73]
	v_add_f32_e32 v4, v68, v4
	v_and_b32_e32 v70, 0xffff0000, v71
	v_lshlrev_b32_e32 v71, 16, v71
	v_add_f32_e32 v4, v73, v4
	v_pk_mul_f32 v[70:71], v[70:71], v[70:71]
	v_add_f32_e32 v4, v72, v4
	v_add_f32_e32 v4, v71, v4
	v_add_f32_e32 v4, v70, v4
	v_add_f32_e32 v70, v74, v4
	v_lshlrev_b32_e32 v4, 16, v64
	v_and_b32_e32 v5, 0xffff0000, v64
	v_pk_mul_f32 v[4:5], v[4:5], v[4:5]
	v_and_b32_e32 v64, 0xffff0000, v65
	v_lshlrev_b32_e32 v65, 16, v65
	v_pk_mul_f32 v[64:65], v[64:65], v[64:65]
	v_add_f32_e32 v4, v4, v5
	v_and_b32_e32 v68, 0xffff0000, v66
	v_lshlrev_b32_e32 v69, 16, v66
	v_add_f32_e32 v4, v65, v4
	v_pk_mul_f32 v[68:69], v[68:69], v[68:69]
	v_add_f32_e32 v4, v64, v4
	v_and_b32_e32 v66, 0xffff0000, v67
	v_lshlrev_b32_e32 v67, 16, v67
	v_add_f32_e32 v4, v69, v4
	v_pk_mul_f32 v[66:67], v[66:67], v[66:67]
	v_add_f32_e32 v4, v68, v4
	v_add_f32_e32 v4, v67, v4
	v_add_f32_e32 v4, v66, v4
	v_add_f32_e32 v4, v70, v4
	s_waitcnt vmcnt(0)
	v_lshlrev_b32_e32 v22, 16, v92
	v_and_b32_e32 v23, 0xffff0000, v92
	v_pk_mul_f32 v[22:23], v[22:23], v[22:23]
	v_and_b32_e32 v92, 0xffff0000, v93
	v_lshlrev_b32_e32 v93, 16, v93
	v_pk_mul_f32 v[92:93], v[92:93], v[92:93]
	v_add_f32_e32 v5, v22, v23
	v_and_b32_e32 v24, 0xffff0000, v94
	v_lshlrev_b32_e32 v25, 16, v94
	v_add_f32_e32 v5, v93, v5
	v_pk_mul_f32 v[24:25], v[24:25], v[24:25]
	v_add_f32_e32 v5, v92, v5
	v_and_b32_e32 v94, 0xffff0000, v95
	v_lshlrev_b32_e32 v95, 16, v95
	v_add_f32_e32 v5, v25, v5
	v_pk_mul_f32 v[94:95], v[94:95], v[94:95]
	v_add_f32_e32 v5, v24, v5
	v_add_f32_e32 v5, v95, v5
	v_add_f32_e32 v5, v94, v5
	v_add_f32_e32 v94, v4, v5
	v_lshlrev_b32_e32 v4, 16, v88
	v_and_b32_e32 v5, 0xffff0000, v88
	v_pk_mul_f32 v[4:5], v[4:5], v[4:5]
	v_and_b32_e32 v88, 0xffff0000, v89
	v_lshlrev_b32_e32 v89, 16, v89
	v_pk_mul_f32 v[88:89], v[88:89], v[88:89]
	v_add_f32_e32 v4, v4, v5
	v_and_b32_e32 v92, 0xffff0000, v90
	v_lshlrev_b32_e32 v93, 16, v90
	v_add_f32_e32 v4, v89, v4
	v_pk_mul_f32 v[92:93], v[92:93], v[92:93]
	v_add_f32_e32 v4, v88, v4
	v_and_b32_e32 v90, 0xffff0000, v91
	v_lshlrev_b32_e32 v91, 16, v91
	v_add_f32_e32 v4, v93, v4
	v_pk_mul_f32 v[90:91], v[90:91], v[90:91]
	v_add_f32_e32 v4, v92, v4
	v_add_f32_e32 v4, v91, v4
	v_add_f32_e32 v4, v90, v4
	v_add_f32_e32 v90, v94, v4
	v_lshlrev_b32_e32 v4, 16, v84
	v_and_b32_e32 v5, 0xffff0000, v84
	v_pk_mul_f32 v[4:5], v[4:5], v[4:5]
	v_and_b32_e32 v84, 0xffff0000, v85
	v_lshlrev_b32_e32 v85, 16, v85
	v_pk_mul_f32 v[84:85], v[84:85], v[84:85]
	v_add_f32_e32 v4, v4, v5
	v_and_b32_e32 v88, 0xffff0000, v86
	v_lshlrev_b32_e32 v89, 16, v86
	v_add_f32_e32 v4, v85, v4
	v_pk_mul_f32 v[88:89], v[88:89], v[88:89]
	v_add_f32_e32 v4, v84, v4
	v_and_b32_e32 v86, 0xffff0000, v87
	v_lshlrev_b32_e32 v87, 16, v87
	v_add_f32_e32 v4, v89, v4
	v_pk_mul_f32 v[86:87], v[86:87], v[86:87]
	v_add_f32_e32 v4, v88, v4
	v_add_f32_e32 v4, v87, v4
	v_add_f32_e32 v4, v86, v4
	v_add_f32_e32 v86, v90, v4
	v_lshlrev_b32_e32 v4, 16, v80
	v_and_b32_e32 v5, 0xffff0000, v80
	v_pk_mul_f32 v[4:5], v[4:5], v[4:5]
	v_and_b32_e32 v80, 0xffff0000, v81
	v_lshlrev_b32_e32 v81, 16, v81
	v_pk_mul_f32 v[80:81], v[80:81], v[80:81]
	v_add_f32_e32 v4, v4, v5
	v_and_b32_e32 v84, 0xffff0000, v82
	v_lshlrev_b32_e32 v85, 16, v82
	v_add_f32_e32 v4, v81, v4
	v_pk_mul_f32 v[84:85], v[84:85], v[84:85]
	v_add_f32_e32 v4, v80, v4
	v_and_b32_e32 v82, 0xffff0000, v83
	v_lshlrev_b32_e32 v83, 16, v83
	v_add_f32_e32 v4, v85, v4
	v_pk_mul_f32 v[82:83], v[82:83], v[82:83]
	v_add_f32_e32 v4, v84, v4
	v_add_f32_e32 v4, v83, v4
	v_add_f32_e32 v4, v82, v4
	v_add_f32_e32 v4, v86, v4
	v_and_b32_e32 v1, 64, v209
	v_xor_b32_e32 v0, 1, v209
	v_add_u32_e32 v1, 64, v1
	v_cmp_lt_i32_e32 vcc, v0, v1
	s_nop 1
	v_cndmask_b32_e32 v0, v209, v0, vcc
	v_lshlrev_b32_e32 v0, 2, v0
	ds_bpermute_b32 v0, v0, v4
	v_cmp_eq_u32_e32 vcc, 0, v3
	s_and_saveexec_b64 s[2:3], vcc
	s_cbranch_execz .LBB0_1027
	s_waitcnt lgkmcnt(0)
	v_add_f32_e32 v0, v4, v0
	v_div_scale_f32 v1, s[16:17], s60, s60, v0
	v_rcp_f32_e32 v3, v1
	v_div_scale_f32 v4, vcc, v0, s60, v0
	v_fma_f32 v5, -v1, v3, 1.0
	v_fmac_f32_e32 v3, v5, v3
	v_mul_f32_e32 v5, v4, v3
	v_fma_f32 v6, -v1, v5, v4
	v_fmac_f32_e32 v5, v6, v3
	v_fma_f32 v1, -v1, v5, v4
	v_div_fmas_f32 v1, v1, v3, v5
	v_div_fixup_f32 v0, v1, s60, v0
	v_add_f32_e32 v0, 0x358637bd, v0
	v_mul_f32_e32 v1, 0x4b800000, v0
	v_cmp_gt_f32_e32 vcc, s33, v0
	s_nop 1
	v_cndmask_b32_e32 v0, v0, v1, vcc
	v_rsq_f32_e32 v0, v0
	v_lshl_add_u32 v1, v2, 2, 16
	v_add_u32_e32 v1, 0x24000, v1
	v_mul_f32_e32 v2, 0x45800000, v0
	v_cndmask_b32_e32 v0, v0, v2, vcc
	ds_write_b32 v1, v0
